# speedup vs baseline: 1.0345x; 1.0083x over previous
; __device__ __forceinline__ int opaque_tid() { int t = threadIdx.x; asm volatile("" : "+v"(t)); return t; }
; #define G_STA(bufoff, gbase, ld) G_STAGE(bufoff, gbase, RA0, RA1, ld)
; #define G_STB(bufoff, gbase, ld) G_STAGE(bufoff, gbase, RB0, RB1, ld)
; #define G_WAIT_V(n) asm volatile("s_waitcnt vmcnt(" #n ")" ::: "memory")
; #define G_BAR __builtin_amdgcn_s_barrier()
; template <bool PERM, class SchedT, class Epi>
; __device__ __forceinline__ void gemm_phase(LAS unsigned char* lds, const SchedT& S, const Epi& E) {
;     const int tid = opaque_tid(), wid = __builtin_amdgcn_readfirstlane(tid >> 6), lane = tid & 63, wr = wid >> 2, wc = wid & 3, fr = lane & 15, fq = lane >> 4;
;     int R0, C0, R1, C1; stage_rc(tid * 16, R0, C0); stage_rc(tid * 16 + 8192, R1, C1);
;     const unsigned RA0 = (unsigned)R0 * 2u, RA1 = (unsigned)R1 * 2u, RB0 = (unsigned)(PERM ? ((R0 & ~31) + perm32(R0 & 31)) : R0) * 2u, RB1 = (unsigned)(PERM ? ((R1 & ~31) + perm32(R1 & 31)) : R1) * 2u;
;     const unsigned CC0 = (unsigned)C0 * 2u, CC1 = (unsigned)C1 * 2u;
;     const size_t kstep = (size_t)(BK * 2);
;     const unsigned ldsw = (unsigned)wid * 1024u;
;     const int aoff = lds_byte(wr * 64 + fr, fq * 8), boff = lds_byte(wc * 32 + fr, fq * 8);
;     ...
;     UnitD cur, nxt; int ui = 0;
;     if (!S.get(0, cur)) return;
;     f32x4 acc[2][2][4][2];
; #pragma unroll
;     for (int a = 0; a < 2; ++a)
; #pragma unroll
;         for (int b = 0; b < 2; ++b)
; #pragma unroll
;             for (int m = 0; m < 4; ++m)
; #pragma unroll
;                 for (int n = 0; n < 2; ++n) acc[a][b][m][n] = (f32x4){0.f, 0.f, 0.f, 0.f};
;     bf16x8 At[4][2], B0[2][2], B1[2][2];
;     const char* cA = cur.A; const char* cB = cur.B;
;     int lda = cur.lda, K = cur.K;
;     ...
;     G_STB(G_SB(0, 0), cB, K); G_STA(G_SA(0, 0), cA, lda); G_STB(G_SB(0, 1), cB + HSTEP(K), K); G_STA(G_SA(0, 1), cA + HSTEP(lda), lda);
;     if (wr == 1) G_BAR;
;     G_WAIT_V(4); G_BAR;
;     G_STB(G_SB(1, 0), cB + kstep, K); G_STA(G_SA(1, 0), cA + kstep, lda); G_STB(G_SB(1, 1), cB + HSTEP(K) + kstep, K);
;     G_WAIT_V(6); G_BAR;
;     __device__ __forceinline__ void operator()(const f32x4 (&acc)[2][2][4][2], const UnitD& u, int wr, int wc, int fr, int fq) const {
;         const int row0 = u.pm * BM + wr * 64 + fr, col0 = u.pn * BM + wc * 32 + 8 * fq;
.LBB0_16:
	v_and_b32_e32 v250, 63, v12
	v_lshrrev_b32_e32 v253, 6, v12
	v_lshlrev_b32_e32 v253, 10, v253
	v_add_u32_e32 v253, 0x22000, v253
	v_and_b32_e32 v254, 15, v250
	v_lshrrev_b32_e32 v255, 4, v250
	v_bfe_u32 v251, v254, 1, 2
	v_xor_b32_e32 v251, v251, v255
	v_lshlrev_b32_e32 v251, 4, v251
	v_lshl_add_u32 v251, v254, 6, v251
	v_add_u32_e32 v251, v251, v253
	v_lshrrev_b32_e32 v254, 2, v250
	v_and_b32_e32 v255, 3, v250
	v_bfe_u32 v252, v254, 1, 2
	v_xor_b32_e32 v252, v252, v255
	v_lshlrev_b32_e32 v252, 4, v252
	v_lshl_add_u32 v252, v254, 6, v252
	v_add_u32_e32 v252, v252, v253
	v_lshlrev_b32_e32 v255, 3, v255
	v_lshlrev_b32_e32 v143, 1, v13
	v_lshrrev_b32_e32 v13, 1, v12
	v_lshlrev_b32_e32 v192, 1, v14
	v_and_b32_e32 v14, 24, v13
	v_readlane_b32 s24, v248, 18
	v_and_b32_e32 v15, 15, v12
	v_lshlrev_b32_e32 v13, 1, v14
	v_lshlrev_b32_e32 v12, 2, v12
	s_lshl_b32 s6, s6, 5
	v_readlane_b32 s25, v248, 19
	v_lshl_or_b32 v193, s7, 6, v254
	v_lshl_or_b32 v13, v15, 6, v13
	s_lshl_b32 s7, s7, 13
	v_and_b32_e32 v12, 32, v12
	s_and_b32 s6, s6, 0x60
	v_lshl_add_u64 v[16:17], s[24:25], 0, v[0:1]
	v_mov_b32_e32 v3, v1
	v_readlane_b32 s22, v248, 22
	v_bitop3_b32 v15, v13, s7, v12 bitop3:0xde
	s_lshl_b32 s7, s6, 7
	v_lshl_add_u64 v[18:19], s[24:25], 0, v[2:3]
	v_mov_b32_e32 v5, v1
	v_readlane_b32 s23, v248, 23
	v_bitop3_b32 v194, v13, s7, v12 bitop3:0xde
	v_lshl_add_u64 v[12:13], v[16:17], 0, s[78:79]
	s_add_i32 m0, s30, 0x18000
	v_lshl_add_u64 v[4:5], s[22:23], 0, v[4:5]
	v_mov_b32_e32 v7, v1
	s_waitcnt vmcnt(4)
	s_barrier
	global_load_lds_dwordx4 v[12:13], off
	v_lshl_add_u64 v[12:13], v[18:19], 0, s[78:79]
	s_add_i32 m0, s30, 0x1a000
	s_add_i32 s36, s30, 0x8000
	v_lshl_add_u64 v[6:7], s[22:23], 0, v[6:7]
	global_load_lds_dwordx4 v[12:13], off
	v_lshl_add_u64 v[4:5], v[4:5], 0, s[78:79]
	s_mov_b32 m0, s36
	s_add_i32 s37, s30, 0xa000
	v_readlane_b32 s8, v248, 26
	global_load_lds_dwordx4 v[4:5], off
	v_lshl_add_u64 v[4:5], v[6:7], 0, s[78:79]
	s_mov_b32 m0, s37
	v_readlane_b32 s9, v248, 27
	global_load_lds_dwordx4 v[4:5], off
	s_nop 0
	v_lshl_add_u64 v[4:5], s[8:9], 0, v[0:1]
	s_add_i32 m0, s30, 0x1c000
	v_lshl_add_u64 v[2:3], s[8:9], 0, v[2:3]
	global_load_lds_dwordx4 v[4:5], off
	s_add_i32 m0, s30, 0x1e000
	v_or_b32_e32 v195, s6, v255
	global_load_lds_dwordx4 v[2:3], off
	v_readlane_b32 s6, v248, 16
	s_waitcnt vmcnt(6)
	v_and_b32_e32 v0, 1, v8
	v_lshlrev_b32_e32 v2, 1, v9
	v_readlane_b32 s7, v248, 17
	v_lshl_add_u32 v0, v0, 6, v2
	v_and_b32_e32 v2, 1, v10
	v_lshlrev_b32_e32 v3, 1, v11
	s_movk_i32 s44, 0x800
	s_mov_b32 s42, s6
	v_readlane_b32 s6, v248, 30
	v_lshl_add_u32 v142, v2, 6, v3
	s_movk_i32 s20, 0x4100
	s_mov_b32 s41, 0
	v_add_u32_e32 v196, 0, v15
	s_mov_b32 s43, s6
	s_mov_b64 s[16:17], s[60:61]
	s_mov_b32 s38, 0
	s_mov_b64 s[12:13], s[22:23]
	s_mov_b64 s[18:19], s[24:25]
	s_mov_b32 s11, s44
	s_barrier
	v_readlane_b32 s7, v248, 31
	s_branch .LBB0_18
.LBB0_17:
	s_and_b64 vcc, exec, s[6:7]
	s_mov_b32 s41, s39
	s_mov_b32 s42, s8
	s_mov_b32 s43, s10
	s_mov_b64 s[16:17], s[14:15]
	s_mov_b32 s44, s11
	s_mov_b32 s20, s40
	s_mov_b64 s[24:25], s[18:19]
	s_mov_b64 s[22:23], s[12:13]
	s_cbranch_vccnz .LBB0_51

; #define G_STA(bufoff, gbase, ld) G_STAGE(bufoff, gbase, RA0, RA1, ld)
; #define G_STB(bufoff, gbase, ld) G_STAGE(bufoff, gbase, RB0, RB1, ld)
; #define G_LDA(dst, b, h) do { _Pragma("unroll") for (int m = 0; m < 4; ++m) _Pragma("unroll") for (int k = 0; k < 2; ++k) dst[m][k] = *(const LAS bf16x8*)(lds + G_SA(b, h) + aoff + m * 2048 + k * 1024); } while (0)
; #define G_LDB(dst, b, h) do { _Pragma("unroll") for (int n = 0; n < 2; ++n) _Pragma("unroll") for (int k = 0; k < 2; ++k) dst[n][k] = *(const LAS bf16x8*)(lds + G_SB(b, h) + boff + n * 2048 + k * 1024); } while (0)
; #define G_MMA(ai, bj, At, Bt) do { __builtin_amdgcn_s_setprio(1); _Pragma("unroll") for (int m = 0; m < 4; ++m) _Pragma("unroll") for (int n = 0; n < 2; ++n) _Pragma("unroll") for (int k = 0; k < 2; ++k) \
;         acc[ai][bj][m][n] = __builtin_amdgcn_mfma_f32_16x16x32_bf16(Bt[n][k], At[m][k], acc[ai][bj][m][n], 0, 0, 0); __builtin_amdgcn_s_setprio(0); } while (0)
; #define G_WAIT_V(n) asm volatile("s_waitcnt vmcnt(" #n ")" ::: "memory")
; #define G_WAIT_L(n) asm volatile("s_waitcnt lgkmcnt(" #n ")" ::: "memory")
; #define G_BAR __builtin_amdgcn_s_barrier()
; #define G_SCHED __builtin_amdgcn_sched_barrier(0)
; template <bool PERM, class SchedT, class Epi>
; __device__ __forceinline__ void gemm_phase(LAS unsigned char* lds, const SchedT& S, const Epi& E) {
;     ...
;         for (int t = 0; t < nt; t += 2) {
;             const bool last = (t == nt - 2);
;             const char* a1 = cA + (size_t)(t + 1) * kstep;
;             const char* a2 = last ? nA : cA + (size_t)(t + 2) * kstep; const char* b2 = last ? nB : cB + (size_t)(t + 2) * kstep;
;             const char* a3 = a2 + kstep; const char* b3 = b2 + kstep;
;             const int wlda = last ? nlda : lda, wK = last ? nK : K;
;             G_LDB(B0, 0, 0); G_SCHED; G_LDA(At, 0, 0); G_STA(G_SA(1, 1), a1 + HSTEP(lda), lda);
;             G_WAIT_L(8); G_BAR; G_WAIT_L(0); G_MMA(0, 0, At, B0); G_BAR; G_SCHED;
;             G_LDB(B1, 0, 1); G_STB(G_SB(0, 0), b2, wK);
;             G_BAR; G_WAIT_L(0); G_MMA(0, 1, At, B1); G_BAR;
;             G_LDA(At, 0, 1); G_STA(G_SA(0, 0), a2, wlda);
;             G_BAR; G_WAIT_L(0); G_MMA(1, 0, At, B0); G_BAR; G_SCHED;
;             G_STB(G_SB(0, 1), b2 + HSTEP(wK), wK);
;             G_WAIT_V(6); G_BAR; G_MMA(1, 1, At, B1); G_BAR;
.LBB0_44:
	s_cmp_eq_u32 s45, s47
	s_cselect_b64 s[28:29], -1, 0
	s_add_i32 s47, s47, 2
	s_add_u32 s26, s22, 0x80
	s_addc_u32 s27, s23, 0
	s_and_b64 s[24:25], s[28:29], exec
	s_cselect_b32 s25, s13, s27
	s_cselect_b32 s24, s12, s26
	s_cselect_b32 s26, s40, s20
	s_add_i32 s27, 0, 0x10000
	v_add_u32_e32 v152, s27, v194
	ds_read_b128 v[134:137], v152
	ds_read_b128 v[144:147], v152 offset:1024
	ds_read_b128 v[148:151], v152 offset:2048
	ds_read_b128 v[152:155], v152 offset:3072
	s_and_b64 s[28:29], s[28:29], exec
	s_cselect_b32 s29, s19, s46
	s_cselect_b32 s28, s18, s21
	s_cselect_b32 s72, s11, s44
	v_lshl_add_u64 v[156:157], s[22:23], 0, v[130:131]
	s_add_i32 m0, s30, 0xc000
	ds_read_b128 v[160:163], v196
	ds_read_b128 v[164:167], v196 offset:1024
	ds_read_b128 v[168:171], v196 offset:2048
	ds_read_b128 v[172:175], v196 offset:3072
	ds_read_b128 v[176:179], v196 offset:4096
	ds_read_b128 v[198:201], v196 offset:5120
	ds_read_b128 v[202:205], v196 offset:6144
	ds_read_b128 v[206:209], v196 offset:7168
	global_load_lds_dwordx4 v[156:157], off
	v_lshl_add_u64 v[156:157], s[22:23], 0, v[132:133]
	s_add_i32 m0, s30, 0xe000
	s_nop 0
	global_load_lds_dwordx4 v[156:157], off
	s_waitcnt lgkmcnt(8)
	s_barrier
	s_waitcnt lgkmcnt(0)
	s_setprio 1
	s_waitcnt lgkmcnt(0)
	v_mfma_f32_16x16x32_bf16 v[126:129], v[134:137], v[160:163], v[126:129]
	v_mfma_f32_16x16x32_bf16 v[122:125], v[148:151], v[160:163], v[122:125]
	v_mfma_f32_16x16x32_bf16 v[118:121], v[134:137], v[168:171], v[118:121]
	v_mfma_f32_16x16x32_bf16 v[114:117], v[148:151], v[168:171], v[114:117]
	v_mfma_f32_16x16x32_bf16 v[102:105], v[134:137], v[176:179], v[102:105]
	v_mfma_f32_16x16x32_bf16 v[98:101], v[148:151], v[176:179], v[98:101]
	v_mfma_f32_16x16x32_bf16 v[86:89], v[134:137], v[202:205], v[86:89]
	v_mfma_f32_16x16x32_bf16 v[82:85], v[148:151], v[202:205], v[82:85]
	v_mfma_f32_16x16x32_bf16 v[126:129], v[144:147], v[164:167], v[126:129]
	v_mfma_f32_16x16x32_bf16 v[122:125], v[152:155], v[164:167], v[122:125]
	v_mfma_f32_16x16x32_bf16 v[118:121], v[144:147], v[172:175], v[118:121]
	v_mfma_f32_16x16x32_bf16 v[114:117], v[152:155], v[172:175], v[114:117]
	v_mfma_f32_16x16x32_bf16 v[102:105], v[144:147], v[198:201], v[102:105]
	v_mfma_f32_16x16x32_bf16 v[98:101], v[152:155], v[198:201], v[98:101]
	v_mfma_f32_16x16x32_bf16 v[86:89], v[144:147], v[206:209], v[86:89]
	v_mfma_f32_16x16x32_bf16 v[82:85], v[152:155], v[206:209], v[82:85]
	s_setprio 0
	s_barrier
	s_add_i32 s50, 0, 0x14000
	v_add_u32_e32 v156, s50, v194
	s_add_i32 s27, s27, s5
	ds_read_b128 v[210:213], v156
	ds_read_b128 v[214:217], v156 offset:1024
	ds_read_b128 v[218:221], v156 offset:2048
	ds_read_b128 v[222:225], v156 offset:3072
	v_mad_u64_u32 v[156:157], s[48:49], v143, s72, v[138:139]
	s_mov_b32 m0, s27
	v_mad_u64_u32 v[230:231], s[48:49], v192, s72, v[140:141]
	global_load_lds_dwordx4 v156, s[28:29]
	s_add_i32 m0, s27, 0x2000
	v_mov_b32_e32 v157, v1
	global_load_lds_dwordx4 v230, s[28:29]
	s_barrier
	s_waitcnt lgkmcnt(0)
	v_mov_b32_e32 v231, v1
	v_lshl_add_u64 v[232:233], s[28:29], 0, v[156:157]
	v_lshl_add_u64 v[234:235], s[28:29], 0, v[230:231]
	s_setprio 1
	s_waitcnt lgkmcnt(0)
	v_mfma_f32_16x16x32_bf16 v[110:113], v[210:213], v[160:163], v[110:113]
	v_mfma_f32_16x16x32_bf16 v[106:109], v[218:221], v[160:163], v[106:109]
	v_mfma_f32_16x16x32_bf16 v[94:97], v[210:213], v[168:171], v[94:97]
	v_mfma_f32_16x16x32_bf16 v[90:93], v[218:221], v[168:171], v[90:93]
	v_mfma_f32_16x16x32_bf16 v[78:81], v[210:213], v[176:179], v[78:81]
	v_mfma_f32_16x16x32_bf16 v[74:77], v[218:221], v[176:179], v[74:77]
	v_mfma_f32_16x16x32_bf16 v[70:73], v[210:213], v[202:205], v[70:73]
	v_mfma_f32_16x16x32_bf16 v[66:69], v[218:221], v[202:205], v[66:69]
	v_mfma_f32_16x16x32_bf16 v[110:113], v[214:217], v[164:167], v[110:113]
	v_mfma_f32_16x16x32_bf16 v[106:109], v[222:225], v[164:167], v[106:109]
	v_mfma_f32_16x16x32_bf16 v[94:97], v[214:217], v[172:175], v[94:97]
	v_mfma_f32_16x16x32_bf16 v[90:93], v[222:225], v[172:175], v[90:93]
	v_mfma_f32_16x16x32_bf16 v[78:81], v[214:217], v[198:201], v[78:81]
	v_mfma_f32_16x16x32_bf16 v[74:77], v[222:225], v[198:201], v[74:77]
	v_mfma_f32_16x16x32_bf16 v[70:73], v[214:217], v[206:209], v[70:73]
	v_mfma_f32_16x16x32_bf16 v[66:69], v[222:225], v[206:209], v[66:69]
	s_setprio 0
	s_mov_b32 m0, s30
	v_mad_u64_u32 v[236:237], s[48:49], s26, v139, v[138:139]
	s_barrier
	ds_read_b128 v[160:163], v196 offset:16384
	ds_read_b128 v[164:167], v196 offset:17408
	ds_read_b128 v[168:171], v196 offset:18432
	ds_read_b128 v[172:175], v196 offset:19456
	ds_read_b128 v[176:179], v196 offset:20480
	ds_read_b128 v[198:201], v196 offset:21504
	ds_read_b128 v[202:205], v196 offset:22528
	ds_read_b128 v[206:209], v196 offset:23552
	global_load_lds_dwordx4 v236, s[24:25]
	v_mad_u64_u32 v[238:239], s[48:49], s26, v141, v[140:141]
	s_mov_b32 m0, s31
	v_mov_b32_e32 v237, v1
	global_load_lds_dwordx4 v238, s[24:25]
	s_barrier
	s_waitcnt lgkmcnt(0)
	v_mov_b32_e32 v239, v1
	v_lshl_add_u64 v[240:241], s[24:25], 0, v[236:237]
	v_lshl_add_u64 v[242:243], s[24:25], 0, v[238:239]
	s_setprio 1
	s_waitcnt lgkmcnt(0)
	v_mfma_f32_16x16x32_bf16 v[62:65], v[134:137], v[160:163], v[62:65]
	v_mfma_f32_16x16x32_bf16 v[58:61], v[148:151], v[160:163], v[58:61]
	v_mfma_f32_16x16x32_bf16 v[54:57], v[134:137], v[168:171], v[54:57]
	v_mfma_f32_16x16x32_bf16 v[50:53], v[148:151], v[168:171], v[50:53]
	v_mfma_f32_16x16x32_bf16 v[38:41], v[134:137], v[176:179], v[38:41]
	v_mfma_f32_16x16x32_bf16 v[34:37], v[148:151], v[176:179], v[34:37]
	v_mfma_f32_16x16x32_bf16 v[22:25], v[134:137], v[202:205], v[22:25]
	v_mfma_f32_16x16x32_bf16 v[18:21], v[148:151], v[202:205], v[18:21]
	v_mfma_f32_16x16x32_bf16 v[62:65], v[144:147], v[164:167], v[62:65]
	v_mfma_f32_16x16x32_bf16 v[58:61], v[152:155], v[164:167], v[58:61]
	v_mfma_f32_16x16x32_bf16 v[54:57], v[144:147], v[172:175], v[54:57]
	v_mfma_f32_16x16x32_bf16 v[50:53], v[152:155], v[172:175], v[50:53]
	v_mfma_f32_16x16x32_bf16 v[38:41], v[144:147], v[198:201], v[38:41]
	v_mfma_f32_16x16x32_bf16 v[34:37], v[152:155], v[198:201], v[34:37]
	v_mfma_f32_16x16x32_bf16 v[22:25], v[144:147], v[206:209], v[22:25]
	v_mfma_f32_16x16x32_bf16 v[18:21], v[152:155], v[206:209], v[18:21]
	s_setprio 0
	s_barrier
; #define G_STA(bufoff, gbase, ld) G_STAGE(bufoff, gbase, RA0, RA1, ld)
; #define G_STB(bufoff, gbase, ld) G_STAGE(bufoff, gbase, RB0, RB1, ld)
; #define G_LDA(dst, b, h) do { _Pragma("unroll") for (int m = 0; m < 4; ++m) _Pragma("unroll") for (int k = 0; k < 2; ++k) dst[m][k] = *(const LAS bf16x8*)(lds + G_SA(b, h) + aoff + m * 2048 + k * 1024); } while (0)
; #define G_LDB(dst, b, h) do { _Pragma("unroll") for (int n = 0; n < 2; ++n) _Pragma("unroll") for (int k = 0; k < 2; ++k) dst[n][k] = *(const LAS bf16x8*)(lds + G_SB(b, h) + boff + n * 2048 + k * 1024); } while (0)
; #define G_MMA(ai, bj, At, Bt) do { __builtin_amdgcn_s_setprio(1); _Pragma("unroll") for (int m = 0; m < 4; ++m) _Pragma("unroll") for (int n = 0; n < 2; ++n) _Pragma("unroll") for (int k = 0; k < 2; ++k) \
;         acc[ai][bj][m][n] = __builtin_amdgcn_mfma_f32_16x16x32_bf16(Bt[n][k], At[m][k], acc[ai][bj][m][n], 0, 0, 0); __builtin_amdgcn_s_setprio(0); } while (0)
; #define G_WAIT_V(n) asm volatile("s_waitcnt vmcnt(" #n ")" ::: "memory")
; #define G_WAIT_L(n) asm volatile("s_waitcnt lgkmcnt(" #n ")" ::: "memory")
; #define G_BAR __builtin_amdgcn_s_barrier()
; #define G_SCHED __builtin_amdgcn_sched_barrier(0)
; template <bool PERM, class SchedT, class Epi>
; __device__ __forceinline__ void gemm_phase(LAS unsigned char* lds, const SchedT& S, const Epi& E) {
;     ...
;             G_STB(G_SB(0, 1), b2 + HSTEP(wK), wK);
;             G_WAIT_V(6); G_BAR; G_MMA(1, 1, At, B1); G_BAR;
;             G_LDB(B0, 1, 0); G_SCHED; G_LDA(At, 1, 0); G_STA(G_SA(0, 1), a2 + HSTEP(wlda), wlda);
;             G_WAIT_L(8); G_BAR; G_WAIT_L(0); G_MMA(0, 0, At, B0); G_BAR; G_SCHED;
;             G_LDB(B1, 1, 1); G_STB(G_SB(1, 0), b3, wK);
;             G_BAR; G_WAIT_L(0); G_MMA(0, 1, At, B1); G_BAR;
;             G_LDA(At, 1, 1); G_STA(G_SA(1, 0), a3, wlda);
;             G_BAR; G_WAIT_L(0); G_MMA(1, 0, At, B0); G_BAR; G_SCHED;
	s_lshl_b64 s[48:49], s[72:73], 8
	s_add_u32 s28, s28, s48
	s_addc_u32 s29, s29, s49
	s_add_i32 s27, s50, s5
	s_mov_b32 m0, s27
	s_nop 0
	global_load_lds_dwordx4 v156, s[28:29]
	s_add_i32 m0, s27, 0x2000
	v_lshl_add_u64 v[156:157], s[28:29], 0, v[156:157]
	global_load_lds_dwordx4 v230, s[28:29]
	s_waitcnt vmcnt(6)
	v_lshl_add_u64 v[230:231], s[28:29], 0, v[230:231]
	s_barrier
	s_setprio 1
	v_mfma_f32_16x16x32_bf16 v[46:49], v[210:213], v[160:163], v[46:49]
	v_mfma_f32_16x16x32_bf16 v[42:45], v[218:221], v[160:163], v[42:45]
	v_mfma_f32_16x16x32_bf16 v[30:33], v[210:213], v[168:171], v[30:33]
	v_mfma_f32_16x16x32_bf16 v[26:29], v[218:221], v[168:171], v[26:29]
	v_mfma_f32_16x16x32_bf16 v[14:17], v[210:213], v[176:179], v[14:17]
	v_mfma_f32_16x16x32_bf16 v[10:13], v[218:221], v[176:179], v[10:13]
	v_mfma_f32_16x16x32_bf16 v[6:9], v[210:213], v[202:205], v[6:9]
	v_mfma_f32_16x16x32_bf16 v[2:5], v[218:221], v[202:205], v[2:5]
	v_mfma_f32_16x16x32_bf16 v[46:49], v[214:217], v[164:167], v[46:49]
	v_mfma_f32_16x16x32_bf16 v[42:45], v[222:225], v[164:167], v[42:45]
	v_mfma_f32_16x16x32_bf16 v[30:33], v[214:217], v[172:175], v[30:33]
	v_mfma_f32_16x16x32_bf16 v[26:29], v[222:225], v[172:175], v[26:29]
	v_mfma_f32_16x16x32_bf16 v[14:17], v[214:217], v[198:201], v[14:17]
	v_mfma_f32_16x16x32_bf16 v[10:13], v[222:225], v[198:201], v[10:13]
	v_mfma_f32_16x16x32_bf16 v[6:9], v[214:217], v[206:209], v[6:9]
	v_mfma_f32_16x16x32_bf16 v[2:5], v[222:225], v[206:209], v[2:5]
	s_setprio 0
	s_add_i32 s28, 0, 0x18000
	v_add_u32_e32 v152, s28, v194
	s_barrier
	ds_read_b128 v[134:137], v152
	ds_read_b128 v[144:147], v152 offset:1024
	ds_read_b128 v[148:151], v152 offset:2048
	ds_read_b128 v[152:155], v152 offset:3072
	s_mov_b32 s27, s73
	s_lshl_b64 s[26:27], s[26:27], 8
	s_add_u32 s24, s24, s26
	s_addc_u32 s25, s25, s27
	s_mov_b32 m0, s34
	ds_read_b128 v[160:163], v196 offset:32768
	ds_read_b128 v[164:167], v196 offset:33792
	ds_read_b128 v[168:171], v196 offset:34816
	ds_read_b128 v[172:175], v196 offset:35840
	ds_read_b128 v[176:179], v196 offset:36864
	ds_read_b128 v[198:201], v196 offset:37888
	ds_read_b128 v[202:205], v196 offset:38912
	ds_read_b128 v[206:209], v196 offset:39936
	global_load_lds_dwordx4 v236, s[24:25]
	s_mov_b32 m0, s35
	s_nop 0
	global_load_lds_dwordx4 v238, s[24:25]
	s_waitcnt lgkmcnt(8)
	s_barrier
	s_waitcnt lgkmcnt(0)
	s_setprio 1
	s_waitcnt lgkmcnt(0)
	v_mfma_f32_16x16x32_bf16 v[126:129], v[134:137], v[160:163], v[126:129]
	v_mfma_f32_16x16x32_bf16 v[122:125], v[148:151], v[160:163], v[122:125]
	v_mfma_f32_16x16x32_bf16 v[118:121], v[134:137], v[168:171], v[118:121]
	v_mfma_f32_16x16x32_bf16 v[114:117], v[148:151], v[168:171], v[114:117]
	v_mfma_f32_16x16x32_bf16 v[102:105], v[134:137], v[176:179], v[102:105]
	v_mfma_f32_16x16x32_bf16 v[98:101], v[148:151], v[176:179], v[98:101]
	v_mfma_f32_16x16x32_bf16 v[86:89], v[134:137], v[202:205], v[86:89]
	v_mfma_f32_16x16x32_bf16 v[82:85], v[148:151], v[202:205], v[82:85]
	v_mfma_f32_16x16x32_bf16 v[126:129], v[144:147], v[164:167], v[126:129]
	v_mfma_f32_16x16x32_bf16 v[122:125], v[152:155], v[164:167], v[122:125]
	v_mfma_f32_16x16x32_bf16 v[118:121], v[144:147], v[172:175], v[118:121]
	v_mfma_f32_16x16x32_bf16 v[114:117], v[152:155], v[172:175], v[114:117]
	v_mfma_f32_16x16x32_bf16 v[102:105], v[144:147], v[198:201], v[102:105]
	v_mfma_f32_16x16x32_bf16 v[98:101], v[152:155], v[198:201], v[98:101]
	v_mfma_f32_16x16x32_bf16 v[86:89], v[144:147], v[206:209], v[86:89]
	v_mfma_f32_16x16x32_bf16 v[82:85], v[152:155], v[206:209], v[82:85]
	s_setprio 0
	s_barrier
	s_add_i32 s24, 0, 0x1c000
	s_add_i32 s25, s28, s5
	v_add_u32_e32 v197, s24, v194
	v_lshl_add_u64 v[232:233], v[232:233], 0, s[78:79]
	s_mov_b32 m0, s25
	ds_read_b128 v[210:213], v197
	ds_read_b128 v[214:217], v197 offset:1024
	ds_read_b128 v[218:221], v197 offset:2048
	ds_read_b128 v[222:225], v197 offset:3072
	global_load_lds_dwordx4 v[232:233], off
	v_lshl_add_u64 v[232:233], v[234:235], 0, s[78:79]
	s_add_i32 m0, s25, 0x2000
	s_nop 0
	global_load_lds_dwordx4 v[232:233], off
	s_barrier
	s_waitcnt lgkmcnt(0)
	s_setprio 1
	s_waitcnt lgkmcnt(0)
	v_mfma_f32_16x16x32_bf16 v[110:113], v[210:213], v[160:163], v[110:113]
	v_mfma_f32_16x16x32_bf16 v[106:109], v[218:221], v[160:163], v[106:109]
	v_mfma_f32_16x16x32_bf16 v[94:97], v[210:213], v[168:171], v[94:97]
	v_mfma_f32_16x16x32_bf16 v[90:93], v[218:221], v[168:171], v[90:93]
	v_mfma_f32_16x16x32_bf16 v[78:81], v[210:213], v[176:179], v[78:81]
	v_mfma_f32_16x16x32_bf16 v[74:77], v[218:221], v[176:179], v[74:77]
	v_mfma_f32_16x16x32_bf16 v[70:73], v[210:213], v[202:205], v[70:73]
	v_mfma_f32_16x16x32_bf16 v[66:69], v[218:221], v[202:205], v[66:69]
	v_mfma_f32_16x16x32_bf16 v[110:113], v[214:217], v[164:167], v[110:113]
	v_mfma_f32_16x16x32_bf16 v[106:109], v[222:225], v[164:167], v[106:109]
	v_mfma_f32_16x16x32_bf16 v[94:97], v[214:217], v[172:175], v[94:97]
	v_mfma_f32_16x16x32_bf16 v[90:93], v[222:225], v[172:175], v[90:93]
	v_mfma_f32_16x16x32_bf16 v[78:81], v[214:217], v[198:201], v[78:81]
	v_mfma_f32_16x16x32_bf16 v[74:77], v[222:225], v[198:201], v[74:77]
	v_mfma_f32_16x16x32_bf16 v[70:73], v[214:217], v[206:209], v[70:73]
	v_mfma_f32_16x16x32_bf16 v[66:69], v[222:225], v[206:209], v[66:69]
	s_setprio 0
	s_mov_b32 m0, s36
	v_lshl_add_u64 v[232:233], v[240:241], 0, s[78:79]
	s_barrier
	ds_read_b128 v[160:163], v196 offset:49152
	ds_read_b128 v[164:167], v196 offset:50176
	ds_read_b128 v[168:171], v196 offset:51200
	ds_read_b128 v[172:175], v196 offset:52224
	ds_read_b128 v[176:179], v196 offset:53248
	ds_read_b128 v[198:201], v196 offset:54272
	ds_read_b128 v[202:205], v196 offset:55296
	ds_read_b128 v[206:209], v196 offset:56320
	global_load_lds_dwordx4 v[232:233], off
	v_lshl_add_u64 v[232:233], v[242:243], 0, s[78:79]
	s_mov_b32 m0, s37
	s_nop 0
	global_load_lds_dwordx4 v[232:233], off
	s_barrier
; #define G_STB(bufoff, gbase, ld) G_STAGE(bufoff, gbase, RB0, RB1, ld)
; template <bool PERM, class SchedT, class Epi>
; __device__ __forceinline__ void gemm_phase(LAS unsigned char* lds, const SchedT& S, const Epi& E) {
;     ...
;             G_BAR; G_WAIT_L(0); G_MMA(1, 0, At, B0); G_BAR; G_SCHED;
;             G_STB(G_SB(1, 1), b3 + HSTEP(wK), wK);
;             G_WAIT_V(6); G_BAR; G_MMA(1, 1, At, B1); G_BAR;
;         }
;     __device__ __forceinline__ void operator()(const f32x4 (&acc)[2][2][4][2], const UnitD& u, int wr, int wc, int fr, int fq) const {
;         const int row0 = u.pm * BM + wr * 64 + fr, col0 = u.pn * BM + wc * 32 + 8 * fq;
;         if (u.kind < 2) {
;             GAS bf16_t* C = (GAS bf16_t*)(unsigned long long)u.C;
; #pragma unroll
;             for (int ai = 0; ai < 2; ++ai)
; #pragma unroll
;                 for (int m = 0; m < 4; ++m) { GAS bf16_t* rowp = C + (size_t)(row0 + ai * HALF + m * 16) * 2048 + col0;
; #pragma unroll
;                     for (int bj = 0; bj < 2; ++bj) { const f32x4 v0 = acc[ai][bj][m][0], v1 = acc[ai][bj][m][1];
;                         u32x4 w; w.x = cvt_pk(v0[0], v0[1]); w.y = cvt_pk(v0[2], v0[3]); w.z = cvt_pk(v1[0], v1[1]); w.w = cvt_pk(v1[2], v1[3]);
;                         *(GAS u32x4*)(rowp + bj * HALF) = w; } }
;         } else {
; #pragma unroll
;             for (int ai = 0; ai < 2; ++ai)
; #pragma unroll
;                 for (int m = 0; m < 4; ++m) { const int row = row0 + ai * HALF + m * 16;
;                     const unsigned char* gp = (const unsigned char*)(proj + (size_t)row * NP + C_G) + col0; const size_t po = (size_t)row * 2048 + col0;
;                     u32x2 g0[2], g1[2], g2[2]; u32x4 a[2], b[2];
; #pragma unroll
;                     for (int bj = 0; bj < 2; ++bj) { g0[bj] = *(const u32x2*)(gp + bj * HALF); g1[bj] = *(const u32x2*)(gp + 2048 + bj * HALF); g2[bj] = *(const u32x2*)(gp + 4096 + bj * HALF);
;                         a[bj] = *(const u32x4*)(PA + po + bj * HALF); b[bj] = *(const u32x4*)(PB + po + bj * HALF); }
; #pragma unroll
;                     for (int bj = 0; bj < 2; ++bj) { float f0[8], f1[8], f2[8], fa[8], fb[8], o[8];
;                         unpack_u8(g0[bj], f0); unpack_u8(g1[bj], f1); unpack_u8(g2[bj], f2); unpack8(a[bj], fa); unpack8(b[bj], fb);
;                         const f32x4 v0 = acc[ai][bj][m][0], v1 = acc[ai][bj][m][1];
; #pragma unroll
	s_waitcnt lgkmcnt(0)
	s_setprio 1
	s_waitcnt lgkmcnt(0)
	v_mfma_f32_16x16x32_bf16 v[62:65], v[134:137], v[160:163], v[62:65]
	v_mfma_f32_16x16x32_bf16 v[58:61], v[148:151], v[160:163], v[58:61]
	v_mfma_f32_16x16x32_bf16 v[54:57], v[134:137], v[168:171], v[54:57]
	v_mfma_f32_16x16x32_bf16 v[50:53], v[148:151], v[168:171], v[50:53]
	v_mfma_f32_16x16x32_bf16 v[38:41], v[134:137], v[176:179], v[38:41]
	v_mfma_f32_16x16x32_bf16 v[34:37], v[148:151], v[176:179], v[34:37]
	v_mfma_f32_16x16x32_bf16 v[22:25], v[134:137], v[202:205], v[22:25]
	v_mfma_f32_16x16x32_bf16 v[18:21], v[148:151], v[202:205], v[18:21]
	v_mfma_f32_16x16x32_bf16 v[62:65], v[144:147], v[164:167], v[62:65]
	v_mfma_f32_16x16x32_bf16 v[58:61], v[152:155], v[164:167], v[58:61]
	v_mfma_f32_16x16x32_bf16 v[54:57], v[144:147], v[172:175], v[54:57]
	v_mfma_f32_16x16x32_bf16 v[50:53], v[152:155], v[172:175], v[50:53]
	v_mfma_f32_16x16x32_bf16 v[38:41], v[144:147], v[198:201], v[38:41]
	v_mfma_f32_16x16x32_bf16 v[34:37], v[152:155], v[198:201], v[34:37]
	v_mfma_f32_16x16x32_bf16 v[22:25], v[144:147], v[206:209], v[22:25]
	v_mfma_f32_16x16x32_bf16 v[18:21], v[152:155], v[206:209], v[18:21]
	s_setprio 0
	s_barrier
	s_add_i32 s24, s24, s5
	v_lshl_add_u64 v[134:135], v[156:157], 0, s[78:79]
	s_mov_b32 m0, s24
	s_nop 0
	global_load_lds_dwordx4 v[134:135], off
	v_lshl_add_u64 v[134:135], v[230:231], 0, s[78:79]
	s_add_i32 m0, s24, 0x2000
	s_nop 0
	global_load_lds_dwordx4 v[134:135], off
	s_waitcnt vmcnt(6)
	s_barrier
	s_setprio 1
	v_mfma_f32_16x16x32_bf16 v[46:49], v[210:213], v[160:163], v[46:49]
	v_mfma_f32_16x16x32_bf16 v[42:45], v[218:221], v[160:163], v[42:45]
	v_mfma_f32_16x16x32_bf16 v[30:33], v[210:213], v[168:171], v[30:33]
	v_mfma_f32_16x16x32_bf16 v[26:29], v[218:221], v[168:171], v[26:29]
	v_mfma_f32_16x16x32_bf16 v[14:17], v[210:213], v[176:179], v[14:17]
	v_mfma_f32_16x16x32_bf16 v[10:13], v[218:221], v[176:179], v[10:13]
	v_mfma_f32_16x16x32_bf16 v[6:9], v[210:213], v[202:205], v[6:9]
	v_mfma_f32_16x16x32_bf16 v[2:5], v[218:221], v[202:205], v[2:5]
	v_mfma_f32_16x16x32_bf16 v[46:49], v[214:217], v[164:167], v[46:49]
	v_mfma_f32_16x16x32_bf16 v[42:45], v[222:225], v[164:167], v[42:45]
	v_mfma_f32_16x16x32_bf16 v[30:33], v[214:217], v[172:175], v[30:33]
	v_mfma_f32_16x16x32_bf16 v[26:29], v[222:225], v[172:175], v[26:29]
	v_mfma_f32_16x16x32_bf16 v[14:17], v[214:217], v[198:201], v[14:17]
	v_mfma_f32_16x16x32_bf16 v[10:13], v[222:225], v[198:201], v[10:13]
	v_mfma_f32_16x16x32_bf16 v[6:9], v[214:217], v[206:209], v[6:9]
	v_mfma_f32_16x16x32_bf16 v[2:5], v[222:225], v[206:209], v[2:5]
	s_setprio 0
	s_add_u32 s22, s22, 0x100
	s_addc_u32 s23, s23, 0
	s_add_u32 s21, s21, 0x100
	s_addc_u32 s46, s46, 0
	s_cmp_ge_u32 s47, s9
	s_barrier
	s_cbranch_scc0 .LBB0_44
	v_lshl_add_u32 v144, s43, 8, v193
	v_lshl_or_b32 v150, s42, 8, v195
	s_cmp_lt_i32 s41, 2
	s_cbranch_scc1 .Lg3_k01
	v_readlane_b32 s20, v249, 2
	v_readlane_b32 s21, v249, 3
	v_lshl_add_u32 v145, v144, 11, v150
	v_lshlrev_b32_e32 v145, 1, v145
	v_mul_lo_u32 v146, v144, s3
	v_add_u32_e32 v146, v146, v150
	v_add_u32_e32 v146, 0x5880, v146
	v_mov_b32_e32 v147, v145
	v_mov_b32_e32 v148, v146
	global_load_dwordx2 v[130:131], v148, s[20:21] offset:-2048
	global_load_dwordx2 v[132:133], v148, s[20:21]
	global_load_dwordx2 v[134:135], v148, s[20:21] offset:2048
	global_load_dwordx2 v[136:137], v148, s[20:21] offset:-1920
	global_load_dwordx2 v[160:161], v148, s[20:21] offset:128
	global_load_dwordx2 v[162:163], v148, s[20:21] offset:2176
	global_load_dwordx4 v[164:167], v147, s[58:59]
	global_load_dwordx4 v[168:171], v147, s[60:61]
	global_load_dwordx4 v[172:175], v147, s[58:59] offset:256
	global_load_dwordx4 v[176:179], v147, s[60:61] offset:256
	v_add_u32_e32 v147, 0x10000, v145
	v_add_u32_e32 v148, 0x82000, v146
	global_load_dwordx2 v[198:199], v148, s[20:21] offset:-2048
	global_load_dwordx2 v[200:201], v148, s[20:21]
	global_load_dwordx2 v[202:203], v148, s[20:21] offset:2048
	global_load_dwordx2 v[204:205], v148, s[20:21] offset:-1920
	global_load_dwordx2 v[206:207], v148, s[20:21] offset:128
	global_load_dwordx2 v[208:209], v148, s[20:21] offset:2176
	global_load_dwordx4 v[210:213], v147, s[58:59]
	global_load_dwordx4 v[214:217], v147, s[60:61]
	global_load_dwordx4 v[218:221], v147, s[58:59] offset:256
	global_load_dwordx4 v[222:225], v147, s[60:61] offset:256
	ds_write_b128 v251, v[126:129]
	ds_read_b128 v[126:129], v252
	ds_write_b128 v251, v[122:125]
	ds_read_b128 v[122:125], v252
	ds_write_b128 v251, v[110:113]
	ds_read_b128 v[110:113], v252
	ds_write_b128 v251, v[106:109]
	ds_read_b128 v[106:109], v252
	v_mov_b32_e32 v149, v145
	s_waitcnt vmcnt(10)
	s_waitcnt lgkmcnt(4)
; __device__ __forceinline__ void unpack8(const u32x4 w, float* f) { f[0] = bflo(w.x); f[1] = bfhi(w.x); f[2] = bflo(w.y); f[3] = bfhi(w.y); f[4] = bflo(w.z); f[5] = bfhi(w.z); f[6] = bflo(w.w); f[7] = bfhi(w.w); }
; __device__ __forceinline__ u32x4 pack8(const float* f) { u32x4 w; w.x = cvt_pk(f[0], f[1]); w.y = cvt_pk(f[2], f[3]); w.z = cvt_pk(f[4], f[5]); w.w = cvt_pk(f[6], f[7]); return w; }
;     __device__ __forceinline__ void operator()(const f32x4 (&acc)[2][2][4][2], const UnitD& u, int wr, int wc, int fr, int fq) const {
;     ...
;             for (int ai = 0; ai < 2; ++ai)
; #pragma unroll
;                 for (int m = 0; m < 4; ++m) { const int row = row0 + ai * HALF + m * 16;
;                     const unsigned char* gp = (const unsigned char*)(proj + (size_t)row * NP + C_G) + col0; const size_t po = (size_t)row * 2048 + col0;
;                     u32x2 g0[2], g1[2], g2[2]; u32x4 a[2], b[2];
; #pragma unroll
;                     for (int bj = 0; bj < 2; ++bj) { g0[bj] = *(const u32x2*)(gp + bj * HALF); g1[bj] = *(const u32x2*)(gp + 2048 + bj * HALF); g2[bj] = *(const u32x2*)(gp + 4096 + bj * HALF);
;                         a[bj] = *(const u32x4*)(PA + po + bj * HALF); b[bj] = *(const u32x4*)(PB + po + bj * HALF); }
; #pragma unroll
;                     for (int bj = 0; bj < 2; ++bj) { float f0[8], f1[8], f2[8], fa[8], fb[8], o[8];
;                         unpack_u8(g0[bj], f0); unpack_u8(g1[bj], f1); unpack_u8(g2[bj], f2); unpack8(a[bj], fa); unpack8(b[bj], fb);
;                         const f32x4 v0 = acc[ai][bj][m][0], v1 = acc[ai][bj][m][1];
; #pragma unroll
;                         for (int j = 0; j < 4; ++j) { o[j] = f0[j] * fa[j] + f1[j] * fb[j] + f2[j] * v0[j]; o[4 + j] = f0[4 + j] * fa[4 + j] + f1[4 + j] * fb[4 + j] + f2[4 + j] * v1[j]; }
;                         *(u32x4*)(H + po + bj * HALF) = pack8(o); } }
	v_cvt_f32_ubyte0_e32 v152, v130
	v_cvt_f32_ubyte0_e32 v153, v132
	v_cvt_f32_ubyte0_e32 v154, v134
	v_lshlrev_b32_e32 v155, 16, v164
	v_lshlrev_b32_e32 v156, 16, v168
	v_mul_f32_e32 v152, 0x3b808081, v152
	v_mul_f32_e32 v153, 0x3b808081, v153
	v_mul_f32_e32 v154, 0x3b808081, v154
	v_mul_f32_e32 v157, v152, v155
	v_fmac_f32_e32 v157, v153, v156
	v_fma_f32 v126, v154, v126, v157
	v_cvt_f32_ubyte1_e32 v152, v130
	v_cvt_f32_ubyte1_e32 v153, v132
	v_cvt_f32_ubyte1_e32 v154, v134
	v_and_b32_e32 v155, 0xffff0000, v164
	v_and_b32_e32 v156, 0xffff0000, v168
	v_mul_f32_e32 v152, 0x3b808081, v152
	v_mul_f32_e32 v153, 0x3b808081, v153
	v_mul_f32_e32 v154, 0x3b808081, v154
	v_mul_f32_e32 v157, v152, v155
	v_fmac_f32_e32 v157, v153, v156
	v_fma_f32 v127, v154, v127, v157
	v_cvt_f32_ubyte2_e32 v152, v130
	v_cvt_f32_ubyte2_e32 v153, v132
	v_cvt_f32_ubyte2_e32 v154, v134
	v_lshlrev_b32_e32 v155, 16, v165
	v_lshlrev_b32_e32 v156, 16, v169
	v_mul_f32_e32 v152, 0x3b808081, v152
	v_mul_f32_e32 v153, 0x3b808081, v153
	v_mul_f32_e32 v154, 0x3b808081, v154
	v_mul_f32_e32 v157, v152, v155
	v_fmac_f32_e32 v157, v153, v156
	v_fma_f32 v128, v154, v128, v157
	v_cvt_f32_ubyte3_e32 v152, v130
	v_cvt_f32_ubyte3_e32 v153, v132
	v_cvt_f32_ubyte3_e32 v154, v134
	v_and_b32_e32 v155, 0xffff0000, v165
	v_and_b32_e32 v156, 0xffff0000, v169
	v_mul_f32_e32 v152, 0x3b808081, v152
	v_mul_f32_e32 v153, 0x3b808081, v153
	v_mul_f32_e32 v154, 0x3b808081, v154
	v_mul_f32_e32 v157, v152, v155
	v_fmac_f32_e32 v157, v153, v156
	v_fma_f32 v129, v154, v129, v157
	v_cvt_f32_ubyte0_e32 v152, v131
	v_cvt_f32_ubyte0_e32 v153, v133
	v_cvt_f32_ubyte0_e32 v154, v135
	v_lshlrev_b32_e32 v155, 16, v166
	v_lshlrev_b32_e32 v156, 16, v170
	v_mul_f32_e32 v152, 0x3b808081, v152
	v_mul_f32_e32 v153, 0x3b808081, v153
	v_mul_f32_e32 v154, 0x3b808081, v154
	v_mul_f32_e32 v157, v152, v155
	v_fmac_f32_e32 v157, v153, v156
	v_fma_f32 v122, v154, v122, v157
	v_cvt_f32_ubyte1_e32 v152, v131
	v_cvt_f32_ubyte1_e32 v153, v133
	v_cvt_f32_ubyte1_e32 v154, v135
	v_and_b32_e32 v155, 0xffff0000, v166
	v_and_b32_e32 v156, 0xffff0000, v170
	v_mul_f32_e32 v152, 0x3b808081, v152
	v_mul_f32_e32 v153, 0x3b808081, v153
	v_mul_f32_e32 v154, 0x3b808081, v154
	v_mul_f32_e32 v157, v152, v155
	v_fmac_f32_e32 v157, v153, v156
	v_fma_f32 v123, v154, v123, v157
	v_cvt_f32_ubyte2_e32 v152, v131
	v_cvt_f32_ubyte2_e32 v153, v133
	v_cvt_f32_ubyte2_e32 v154, v135
	v_lshlrev_b32_e32 v155, 16, v167
	v_lshlrev_b32_e32 v156, 16, v171
	v_mul_f32_e32 v152, 0x3b808081, v152
	v_mul_f32_e32 v153, 0x3b808081, v153
	v_mul_f32_e32 v154, 0x3b808081, v154
	v_mul_f32_e32 v157, v152, v155
	v_fmac_f32_e32 v157, v153, v156
	v_fma_f32 v124, v154, v124, v157
	v_cvt_f32_ubyte3_e32 v152, v131
	v_cvt_f32_ubyte3_e32 v153, v133
	v_cvt_f32_ubyte3_e32 v154, v135
	v_and_b32_e32 v155, 0xffff0000, v167
	v_and_b32_e32 v156, 0xffff0000, v171
	v_mul_f32_e32 v152, 0x3b808081, v152
	v_mul_f32_e32 v153, 0x3b808081, v153
	v_mul_f32_e32 v154, 0x3b808081, v154
	v_mul_f32_e32 v157, v152, v155
	v_fmac_f32_e32 v157, v153, v156
	v_fma_f32 v125, v154, v125, v157
	v_cvt_pk_bf16_f32 v126, v126, v127
	v_cvt_pk_bf16_f32 v127, v128, v129
	v_cvt_pk_bf16_f32 v128, v122, v123
	v_cvt_pk_bf16_f32 v129, v124, v125
	global_store_dwordx4 v149, v[126:129], s[62:63]
	s_waitcnt lgkmcnt(0)
	v_cvt_f32_ubyte0_e32 v152, v136
	v_cvt_f32_ubyte0_e32 v153, v160
	v_cvt_f32_ubyte0_e32 v154, v162
	v_lshlrev_b32_e32 v155, 16, v172
	v_lshlrev_b32_e32 v156, 16, v176
	v_mul_f32_e32 v152, 0x3b808081, v152
	v_mul_f32_e32 v153, 0x3b808081, v153
	v_mul_f32_e32 v154, 0x3b808081, v154
	v_mul_f32_e32 v157, v152, v155
	v_fmac_f32_e32 v157, v153, v156
	v_fma_f32 v110, v154, v110, v157
	v_cvt_f32_ubyte1_e32 v152, v136
	v_cvt_f32_ubyte1_e32 v153, v160
	v_cvt_f32_ubyte1_e32 v154, v162
	v_and_b32_e32 v155, 0xffff0000, v172
	v_and_b32_e32 v156, 0xffff0000, v176
	v_mul_f32_e32 v152, 0x3b808081, v152
	v_mul_f32_e32 v153, 0x3b808081, v153
	v_mul_f32_e32 v154, 0x3b808081, v154
	v_mul_f32_e32 v157, v152, v155
	v_fmac_f32_e32 v157, v153, v156
	v_fma_f32 v111, v154, v111, v157
	v_cvt_f32_ubyte2_e32 v152, v136
	v_cvt_f32_ubyte2_e32 v153, v160
	v_cvt_f32_ubyte2_e32 v154, v162
	v_lshlrev_b32_e32 v155, 16, v173
	v_lshlrev_b32_e32 v156, 16, v177
	v_mul_f32_e32 v152, 0x3b808081, v152
	v_mul_f32_e32 v153, 0x3b808081, v153
	v_mul_f32_e32 v154, 0x3b808081, v154
	v_mul_f32_e32 v157, v152, v155
	v_fmac_f32_e32 v157, v153, v156
	v_fma_f32 v112, v154, v112, v157
	v_cvt_f32_ubyte3_e32 v152, v136
	v_cvt_f32_ubyte3_e32 v153, v160
	v_cvt_f32_ubyte3_e32 v154, v162
	v_and_b32_e32 v155, 0xffff0000, v173
	v_and_b32_e32 v156, 0xffff0000, v177
	v_mul_f32_e32 v152, 0x3b808081, v152
	v_mul_f32_e32 v153, 0x3b808081, v153
	v_mul_f32_e32 v154, 0x3b808081, v154
	v_mul_f32_e32 v157, v152, v155
	v_fmac_f32_e32 v157, v153, v156
	v_fma_f32 v113, v154, v113, v157
	v_cvt_f32_ubyte0_e32 v152, v137
	v_cvt_f32_ubyte0_e32 v153, v161
	v_cvt_f32_ubyte0_e32 v154, v163
	v_lshlrev_b32_e32 v155, 16, v174
	v_lshlrev_b32_e32 v156, 16, v178
	v_mul_f32_e32 v152, 0x3b808081, v152
	v_mul_f32_e32 v153, 0x3b808081, v153
	v_mul_f32_e32 v154, 0x3b808081, v154
	v_mul_f32_e32 v157, v152, v155
	v_fmac_f32_e32 v157, v153, v156
	v_fma_f32 v106, v154, v106, v157
	v_cvt_f32_ubyte1_e32 v152, v137
	v_cvt_f32_ubyte1_e32 v153, v161
	v_cvt_f32_ubyte1_e32 v154, v163
	v_and_b32_e32 v155, 0xffff0000, v174
	v_and_b32_e32 v156, 0xffff0000, v178
	v_mul_f32_e32 v152, 0x3b808081, v152
	v_mul_f32_e32 v153, 0x3b808081, v153
	v_mul_f32_e32 v154, 0x3b808081, v154
	v_mul_f32_e32 v157, v152, v155
	v_fmac_f32_e32 v157, v153, v156
	v_fma_f32 v107, v154, v107, v157
	v_cvt_f32_ubyte2_e32 v152, v137
; __device__ __forceinline__ void unpack8(const u32x4 w, float* f) { f[0] = bflo(w.x); f[1] = bfhi(w.x); f[2] = bflo(w.y); f[3] = bfhi(w.y); f[4] = bflo(w.z); f[5] = bfhi(w.z); f[6] = bflo(w.w); f[7] = bfhi(w.w); }
; __device__ __forceinline__ u32x4 pack8(const float* f) { u32x4 w; w.x = cvt_pk(f[0], f[1]); w.y = cvt_pk(f[2], f[3]); w.z = cvt_pk(f[4], f[5]); w.w = cvt_pk(f[6], f[7]); return w; }
;     __device__ __forceinline__ void operator()(const f32x4 (&acc)[2][2][4][2], const UnitD& u, int wr, int wc, int fr, int fq) const {
;     ...
;             for (int ai = 0; ai < 2; ++ai)
; #pragma unroll
;                 for (int m = 0; m < 4; ++m) { const int row = row0 + ai * HALF + m * 16;
;                     const unsigned char* gp = (const unsigned char*)(proj + (size_t)row * NP + C_G) + col0; const size_t po = (size_t)row * 2048 + col0;
;                     u32x2 g0[2], g1[2], g2[2]; u32x4 a[2], b[2];
; #pragma unroll
;                     for (int bj = 0; bj < 2; ++bj) { g0[bj] = *(const u32x2*)(gp + bj * HALF); g1[bj] = *(const u32x2*)(gp + 2048 + bj * HALF); g2[bj] = *(const u32x2*)(gp + 4096 + bj * HALF);
;                         a[bj] = *(const u32x4*)(PA + po + bj * HALF); b[bj] = *(const u32x4*)(PB + po + bj * HALF); }
; #pragma unroll
;                     for (int bj = 0; bj < 2; ++bj) { float f0[8], f1[8], f2[8], fa[8], fb[8], o[8];
;                         unpack_u8(g0[bj], f0); unpack_u8(g1[bj], f1); unpack_u8(g2[bj], f2); unpack8(a[bj], fa); unpack8(b[bj], fb);
;                         const f32x4 v0 = acc[ai][bj][m][0], v1 = acc[ai][bj][m][1];
; #pragma unroll
;                         for (int j = 0; j < 4; ++j) { o[j] = f0[j] * fa[j] + f1[j] * fb[j] + f2[j] * v0[j]; o[4 + j] = f0[4 + j] * fa[4 + j] + f1[4 + j] * fb[4 + j] + f2[4 + j] * v1[j]; }
;                         *(u32x4*)(H + po + bj * HALF) = pack8(o); } }
	v_cvt_f32_ubyte2_e32 v153, v161
	v_cvt_f32_ubyte2_e32 v154, v163
	v_lshlrev_b32_e32 v155, 16, v175
	v_lshlrev_b32_e32 v156, 16, v179
	v_mul_f32_e32 v152, 0x3b808081, v152
	v_mul_f32_e32 v153, 0x3b808081, v153
	v_mul_f32_e32 v154, 0x3b808081, v154
	v_mul_f32_e32 v157, v152, v155
	v_fmac_f32_e32 v157, v153, v156
	v_fma_f32 v108, v154, v108, v157
	v_cvt_f32_ubyte3_e32 v152, v137
	v_cvt_f32_ubyte3_e32 v153, v161
	v_cvt_f32_ubyte3_e32 v154, v163
	v_and_b32_e32 v155, 0xffff0000, v175
	v_and_b32_e32 v156, 0xffff0000, v179
	v_mul_f32_e32 v152, 0x3b808081, v152
	v_mul_f32_e32 v153, 0x3b808081, v153
	v_mul_f32_e32 v154, 0x3b808081, v154
	v_mul_f32_e32 v157, v152, v155
	v_fmac_f32_e32 v157, v153, v156
	v_fma_f32 v109, v154, v109, v157
	v_cvt_pk_bf16_f32 v110, v110, v111
	v_cvt_pk_bf16_f32 v111, v112, v113
	v_cvt_pk_bf16_f32 v112, v106, v107
	v_cvt_pk_bf16_f32 v113, v108, v109
	global_store_dwordx4 v149, v[110:113], s[62:63] offset:256
	v_add_u32_e32 v147, 0x20000, v145
	v_add_u32_e32 v148, 0x104000, v146
	global_load_dwordx2 v[130:131], v148, s[20:21] offset:-2048
	global_load_dwordx2 v[132:133], v148, s[20:21]
	global_load_dwordx2 v[134:135], v148, s[20:21] offset:2048
	global_load_dwordx2 v[136:137], v148, s[20:21] offset:-1920
	global_load_dwordx2 v[160:161], v148, s[20:21] offset:128
	global_load_dwordx2 v[162:163], v148, s[20:21] offset:2176
	global_load_dwordx4 v[164:167], v147, s[58:59]
	global_load_dwordx4 v[168:171], v147, s[60:61]
	global_load_dwordx4 v[172:175], v147, s[58:59] offset:256
	global_load_dwordx4 v[176:179], v147, s[60:61] offset:256
	ds_write_b128 v251, v[118:121]
	ds_read_b128 v[118:121], v252
	ds_write_b128 v251, v[114:117]
	ds_read_b128 v[114:117], v252
	ds_write_b128 v251, v[94:97]
	ds_read_b128 v[94:97], v252
	ds_write_b128 v251, v[90:93]
	ds_read_b128 v[90:93], v252
	v_add_u32_e32 v149, 0x10000, v145
	s_waitcnt vmcnt(12)
	s_waitcnt lgkmcnt(4)
	v_cvt_f32_ubyte0_e32 v152, v198
	v_cvt_f32_ubyte0_e32 v153, v200
	v_cvt_f32_ubyte0_e32 v154, v202
	v_lshlrev_b32_e32 v155, 16, v210
	v_lshlrev_b32_e32 v156, 16, v214
	v_mul_f32_e32 v152, 0x3b808081, v152
	v_mul_f32_e32 v153, 0x3b808081, v153
	v_mul_f32_e32 v154, 0x3b808081, v154
	v_mul_f32_e32 v157, v152, v155
	v_fmac_f32_e32 v157, v153, v156
	v_fma_f32 v118, v154, v118, v157
	v_cvt_f32_ubyte1_e32 v152, v198
	v_cvt_f32_ubyte1_e32 v153, v200
	v_cvt_f32_ubyte1_e32 v154, v202
	v_and_b32_e32 v155, 0xffff0000, v210
	v_and_b32_e32 v156, 0xffff0000, v214
	v_mul_f32_e32 v152, 0x3b808081, v152
	v_mul_f32_e32 v153, 0x3b808081, v153
	v_mul_f32_e32 v154, 0x3b808081, v154
	v_mul_f32_e32 v157, v152, v155
	v_fmac_f32_e32 v157, v153, v156
	v_fma_f32 v119, v154, v119, v157
	v_cvt_f32_ubyte2_e32 v152, v198
	v_cvt_f32_ubyte2_e32 v153, v200
	v_cvt_f32_ubyte2_e32 v154, v202
	v_lshlrev_b32_e32 v155, 16, v211
	v_lshlrev_b32_e32 v156, 16, v215
	v_mul_f32_e32 v152, 0x3b808081, v152
	v_mul_f32_e32 v153, 0x3b808081, v153
	v_mul_f32_e32 v154, 0x3b808081, v154
	v_mul_f32_e32 v157, v152, v155
	v_fmac_f32_e32 v157, v153, v156
	v_fma_f32 v120, v154, v120, v157
	v_cvt_f32_ubyte3_e32 v152, v198
	v_cvt_f32_ubyte3_e32 v153, v200
	v_cvt_f32_ubyte3_e32 v154, v202
	v_and_b32_e32 v155, 0xffff0000, v211
	v_and_b32_e32 v156, 0xffff0000, v215
	v_mul_f32_e32 v152, 0x3b808081, v152
	v_mul_f32_e32 v153, 0x3b808081, v153
	v_mul_f32_e32 v154, 0x3b808081, v154
	v_mul_f32_e32 v157, v152, v155
	v_fmac_f32_e32 v157, v153, v156
	v_fma_f32 v121, v154, v121, v157
	v_cvt_f32_ubyte0_e32 v152, v199
	v_cvt_f32_ubyte0_e32 v153, v201
	v_cvt_f32_ubyte0_e32 v154, v203
	v_lshlrev_b32_e32 v155, 16, v212
	v_lshlrev_b32_e32 v156, 16, v216
	v_mul_f32_e32 v152, 0x3b808081, v152
	v_mul_f32_e32 v153, 0x3b808081, v153
	v_mul_f32_e32 v154, 0x3b808081, v154
	v_mul_f32_e32 v157, v152, v155
	v_fmac_f32_e32 v157, v153, v156
	v_fma_f32 v114, v154, v114, v157
	v_cvt_f32_ubyte1_e32 v152, v199
	v_cvt_f32_ubyte1_e32 v153, v201
	v_cvt_f32_ubyte1_e32 v154, v203
	v_and_b32_e32 v155, 0xffff0000, v212
	v_and_b32_e32 v156, 0xffff0000, v216
	v_mul_f32_e32 v152, 0x3b808081, v152
	v_mul_f32_e32 v153, 0x3b808081, v153
	v_mul_f32_e32 v154, 0x3b808081, v154
	v_mul_f32_e32 v157, v152, v155
	v_fmac_f32_e32 v157, v153, v156
	v_fma_f32 v115, v154, v115, v157
	v_cvt_f32_ubyte2_e32 v152, v199
	v_cvt_f32_ubyte2_e32 v153, v201
	v_cvt_f32_ubyte2_e32 v154, v203
	v_lshlrev_b32_e32 v155, 16, v213
	v_lshlrev_b32_e32 v156, 16, v217
	v_mul_f32_e32 v152, 0x3b808081, v152
	v_mul_f32_e32 v153, 0x3b808081, v153
	v_mul_f32_e32 v154, 0x3b808081, v154
	v_mul_f32_e32 v157, v152, v155
	v_fmac_f32_e32 v157, v153, v156
	v_fma_f32 v116, v154, v116, v157
	v_cvt_f32_ubyte3_e32 v152, v199
	v_cvt_f32_ubyte3_e32 v153, v201
	v_cvt_f32_ubyte3_e32 v154, v203
	v_and_b32_e32 v155, 0xffff0000, v213
	v_and_b32_e32 v156, 0xffff0000, v217
	v_mul_f32_e32 v152, 0x3b808081, v152
	v_mul_f32_e32 v153, 0x3b808081, v153
	v_mul_f32_e32 v154, 0x3b808081, v154
	v_mul_f32_e32 v157, v152, v155
	v_fmac_f32_e32 v157, v153, v156
	v_fma_f32 v117, v154, v117, v157
	v_cvt_pk_bf16_f32 v118, v118, v119
	v_cvt_pk_bf16_f32 v119, v120, v121
	v_cvt_pk_bf16_f32 v120, v114, v115
	v_cvt_pk_bf16_f32 v121, v116, v117
	global_store_dwordx4 v149, v[118:121], s[62:63]
	s_waitcnt lgkmcnt(0)
; __device__ __forceinline__ void unpack8(const u32x4 w, float* f) { f[0] = bflo(w.x); f[1] = bfhi(w.x); f[2] = bflo(w.y); f[3] = bfhi(w.y); f[4] = bflo(w.z); f[5] = bfhi(w.z); f[6] = bflo(w.w); f[7] = bfhi(w.w); }
; __device__ __forceinline__ u32x4 pack8(const float* f) { u32x4 w; w.x = cvt_pk(f[0], f[1]); w.y = cvt_pk(f[2], f[3]); w.z = cvt_pk(f[4], f[5]); w.w = cvt_pk(f[6], f[7]); return w; }
;     __device__ __forceinline__ void operator()(const f32x4 (&acc)[2][2][4][2], const UnitD& u, int wr, int wc, int fr, int fq) const {
;     ...
;             for (int ai = 0; ai < 2; ++ai)
; #pragma unroll
;                 for (int m = 0; m < 4; ++m) { const int row = row0 + ai * HALF + m * 16;
;                     const unsigned char* gp = (const unsigned char*)(proj + (size_t)row * NP + C_G) + col0; const size_t po = (size_t)row * 2048 + col0;
;                     u32x2 g0[2], g1[2], g2[2]; u32x4 a[2], b[2];
; #pragma unroll
;                     for (int bj = 0; bj < 2; ++bj) { g0[bj] = *(const u32x2*)(gp + bj * HALF); g1[bj] = *(const u32x2*)(gp + 2048 + bj * HALF); g2[bj] = *(const u32x2*)(gp + 4096 + bj * HALF);
;                         a[bj] = *(const u32x4*)(PA + po + bj * HALF); b[bj] = *(const u32x4*)(PB + po + bj * HALF); }
; #pragma unroll
;                     for (int bj = 0; bj < 2; ++bj) { float f0[8], f1[8], f2[8], fa[8], fb[8], o[8];
;                         unpack_u8(g0[bj], f0); unpack_u8(g1[bj], f1); unpack_u8(g2[bj], f2); unpack8(a[bj], fa); unpack8(b[bj], fb);
;                         const f32x4 v0 = acc[ai][bj][m][0], v1 = acc[ai][bj][m][1];
; #pragma unroll
;                         for (int j = 0; j < 4; ++j) { o[j] = f0[j] * fa[j] + f1[j] * fb[j] + f2[j] * v0[j]; o[4 + j] = f0[4 + j] * fa[4 + j] + f1[4 + j] * fb[4 + j] + f2[4 + j] * v1[j]; }
;                         *(u32x4*)(H + po + bj * HALF) = pack8(o); } }
	v_cvt_f32_ubyte0_e32 v152, v204
	v_cvt_f32_ubyte0_e32 v153, v206
	v_cvt_f32_ubyte0_e32 v154, v208
	v_lshlrev_b32_e32 v155, 16, v218
	v_lshlrev_b32_e32 v156, 16, v222
	v_mul_f32_e32 v152, 0x3b808081, v152
	v_mul_f32_e32 v153, 0x3b808081, v153
	v_mul_f32_e32 v154, 0x3b808081, v154
	v_mul_f32_e32 v157, v152, v155
	v_fmac_f32_e32 v157, v153, v156
	v_fma_f32 v94, v154, v94, v157
	v_cvt_f32_ubyte1_e32 v152, v204
	v_cvt_f32_ubyte1_e32 v153, v206
	v_cvt_f32_ubyte1_e32 v154, v208
	v_and_b32_e32 v155, 0xffff0000, v218
	v_and_b32_e32 v156, 0xffff0000, v222
	v_mul_f32_e32 v152, 0x3b808081, v152
	v_mul_f32_e32 v153, 0x3b808081, v153
	v_mul_f32_e32 v154, 0x3b808081, v154
	v_mul_f32_e32 v157, v152, v155
	v_fmac_f32_e32 v157, v153, v156
	v_fma_f32 v95, v154, v95, v157
	v_cvt_f32_ubyte2_e32 v152, v204
	v_cvt_f32_ubyte2_e32 v153, v206
	v_cvt_f32_ubyte2_e32 v154, v208
	v_lshlrev_b32_e32 v155, 16, v219
	v_lshlrev_b32_e32 v156, 16, v223
	v_mul_f32_e32 v152, 0x3b808081, v152
	v_mul_f32_e32 v153, 0x3b808081, v153
	v_mul_f32_e32 v154, 0x3b808081, v154
	v_mul_f32_e32 v157, v152, v155
	v_fmac_f32_e32 v157, v153, v156
	v_fma_f32 v96, v154, v96, v157
	v_cvt_f32_ubyte3_e32 v152, v204
	v_cvt_f32_ubyte3_e32 v153, v206
	v_cvt_f32_ubyte3_e32 v154, v208
	v_and_b32_e32 v155, 0xffff0000, v219
	v_and_b32_e32 v156, 0xffff0000, v223
	v_mul_f32_e32 v152, 0x3b808081, v152
	v_mul_f32_e32 v153, 0x3b808081, v153
	v_mul_f32_e32 v154, 0x3b808081, v154
	v_mul_f32_e32 v157, v152, v155
	v_fmac_f32_e32 v157, v153, v156
	v_fma_f32 v97, v154, v97, v157
	v_cvt_f32_ubyte0_e32 v152, v205
	v_cvt_f32_ubyte0_e32 v153, v207
	v_cvt_f32_ubyte0_e32 v154, v209
	v_lshlrev_b32_e32 v155, 16, v220
	v_lshlrev_b32_e32 v156, 16, v224
	v_mul_f32_e32 v152, 0x3b808081, v152
	v_mul_f32_e32 v153, 0x3b808081, v153
	v_mul_f32_e32 v154, 0x3b808081, v154
	v_mul_f32_e32 v157, v152, v155
	v_fmac_f32_e32 v157, v153, v156
	v_fma_f32 v90, v154, v90, v157
	v_cvt_f32_ubyte1_e32 v152, v205
	v_cvt_f32_ubyte1_e32 v153, v207
	v_cvt_f32_ubyte1_e32 v154, v209
	v_and_b32_e32 v155, 0xffff0000, v220
	v_and_b32_e32 v156, 0xffff0000, v224
	v_mul_f32_e32 v152, 0x3b808081, v152
	v_mul_f32_e32 v153, 0x3b808081, v153
	v_mul_f32_e32 v154, 0x3b808081, v154
	v_mul_f32_e32 v157, v152, v155
	v_fmac_f32_e32 v157, v153, v156
	v_fma_f32 v91, v154, v91, v157
	v_cvt_f32_ubyte2_e32 v152, v205
	v_cvt_f32_ubyte2_e32 v153, v207
	v_cvt_f32_ubyte2_e32 v154, v209
	v_lshlrev_b32_e32 v155, 16, v221
	v_lshlrev_b32_e32 v156, 16, v225
	v_mul_f32_e32 v152, 0x3b808081, v152
	v_mul_f32_e32 v153, 0x3b808081, v153
	v_mul_f32_e32 v154, 0x3b808081, v154
	v_mul_f32_e32 v157, v152, v155
	v_fmac_f32_e32 v157, v153, v156
	v_fma_f32 v92, v154, v92, v157
	v_cvt_f32_ubyte3_e32 v152, v205
	v_cvt_f32_ubyte3_e32 v153, v207
	v_cvt_f32_ubyte3_e32 v154, v209
	v_and_b32_e32 v155, 0xffff0000, v221
	v_and_b32_e32 v156, 0xffff0000, v225
	v_mul_f32_e32 v152, 0x3b808081, v152
	v_mul_f32_e32 v153, 0x3b808081, v153
	v_mul_f32_e32 v154, 0x3b808081, v154
	v_mul_f32_e32 v157, v152, v155
	v_fmac_f32_e32 v157, v153, v156
	v_fma_f32 v93, v154, v93, v157
	v_cvt_pk_bf16_f32 v94, v94, v95
	v_cvt_pk_bf16_f32 v95, v96, v97
	v_cvt_pk_bf16_f32 v96, v90, v91
	v_cvt_pk_bf16_f32 v97, v92, v93
	global_store_dwordx4 v149, v[94:97], s[62:63] offset:256
	v_add_u32_e32 v147, 0x30000, v145
	v_add_u32_e32 v148, 0x186000, v146
	global_load_dwordx2 v[198:199], v148, s[20:21] offset:-2048
	global_load_dwordx2 v[200:201], v148, s[20:21]
	global_load_dwordx2 v[202:203], v148, s[20:21] offset:2048
	global_load_dwordx2 v[204:205], v148, s[20:21] offset:-1920
	global_load_dwordx2 v[206:207], v148, s[20:21] offset:128
	global_load_dwordx2 v[208:209], v148, s[20:21] offset:2176
	global_load_dwordx4 v[210:213], v147, s[58:59]
	global_load_dwordx4 v[214:217], v147, s[60:61]
	global_load_dwordx4 v[218:221], v147, s[58:59] offset:256
	global_load_dwordx4 v[222:225], v147, s[60:61] offset:256
	ds_write_b128 v251, v[102:105]
	ds_read_b128 v[102:105], v252
	ds_write_b128 v251, v[98:101]
	ds_read_b128 v[98:101], v252
	ds_write_b128 v251, v[78:81]
	ds_read_b128 v[78:81], v252
	ds_write_b128 v251, v[74:77]
	ds_read_b128 v[74:77], v252
	v_add_u32_e32 v149, 0x20000, v145
	s_waitcnt vmcnt(12)
	s_waitcnt lgkmcnt(4)
	v_cvt_f32_ubyte0_e32 v152, v130
	v_cvt_f32_ubyte0_e32 v153, v132
	v_cvt_f32_ubyte0_e32 v154, v134
	v_lshlrev_b32_e32 v155, 16, v164
	v_lshlrev_b32_e32 v156, 16, v168
	v_mul_f32_e32 v152, 0x3b808081, v152
	v_mul_f32_e32 v153, 0x3b808081, v153
	v_mul_f32_e32 v154, 0x3b808081, v154
	v_mul_f32_e32 v157, v152, v155
	v_fmac_f32_e32 v157, v153, v156
	v_fma_f32 v102, v154, v102, v157
	v_cvt_f32_ubyte1_e32 v152, v130
	v_cvt_f32_ubyte1_e32 v153, v132
	v_cvt_f32_ubyte1_e32 v154, v134
	v_and_b32_e32 v155, 0xffff0000, v164
	v_and_b32_e32 v156, 0xffff0000, v168
	v_mul_f32_e32 v152, 0x3b808081, v152
	v_mul_f32_e32 v153, 0x3b808081, v153
	v_mul_f32_e32 v154, 0x3b808081, v154
	v_mul_f32_e32 v157, v152, v155
	v_fmac_f32_e32 v157, v153, v156
	v_fma_f32 v103, v154, v103, v157
	v_cvt_f32_ubyte2_e32 v152, v130
	v_cvt_f32_ubyte2_e32 v153, v132
	v_cvt_f32_ubyte2_e32 v154, v134
	v_lshlrev_b32_e32 v155, 16, v165
	v_lshlrev_b32_e32 v156, 16, v169
	v_mul_f32_e32 v152, 0x3b808081, v152
	v_mul_f32_e32 v153, 0x3b808081, v153
	v_mul_f32_e32 v154, 0x3b808081, v154
	v_mul_f32_e32 v157, v152, v155
	v_fmac_f32_e32 v157, v153, v156
	v_fma_f32 v104, v154, v104, v157
	v_cvt_f32_ubyte3_e32 v152, v130
	v_cvt_f32_ubyte3_e32 v153, v132
	v_cvt_f32_ubyte3_e32 v154, v134
	v_and_b32_e32 v155, 0xffff0000, v165
	v_and_b32_e32 v156, 0xffff0000, v169
	v_mul_f32_e32 v152, 0x3b808081, v152
	v_mul_f32_e32 v153, 0x3b808081, v153
	v_mul_f32_e32 v154, 0x3b808081, v154
; __device__ __forceinline__ void unpack8(const u32x4 w, float* f) { f[0] = bflo(w.x); f[1] = bfhi(w.x); f[2] = bflo(w.y); f[3] = bfhi(w.y); f[4] = bflo(w.z); f[5] = bfhi(w.z); f[6] = bflo(w.w); f[7] = bfhi(w.w); }
; __device__ __forceinline__ u32x4 pack8(const float* f) { u32x4 w; w.x = cvt_pk(f[0], f[1]); w.y = cvt_pk(f[2], f[3]); w.z = cvt_pk(f[4], f[5]); w.w = cvt_pk(f[6], f[7]); return w; }
;     __device__ __forceinline__ void operator()(const f32x4 (&acc)[2][2][4][2], const UnitD& u, int wr, int wc, int fr, int fq) const {
;     ...
;             for (int ai = 0; ai < 2; ++ai)
; #pragma unroll
;                 for (int m = 0; m < 4; ++m) { const int row = row0 + ai * HALF + m * 16;
;                     const unsigned char* gp = (const unsigned char*)(proj + (size_t)row * NP + C_G) + col0; const size_t po = (size_t)row * 2048 + col0;
;                     u32x2 g0[2], g1[2], g2[2]; u32x4 a[2], b[2];
; #pragma unroll
;                     for (int bj = 0; bj < 2; ++bj) { g0[bj] = *(const u32x2*)(gp + bj * HALF); g1[bj] = *(const u32x2*)(gp + 2048 + bj * HALF); g2[bj] = *(const u32x2*)(gp + 4096 + bj * HALF);
;                         a[bj] = *(const u32x4*)(PA + po + bj * HALF); b[bj] = *(const u32x4*)(PB + po + bj * HALF); }
; #pragma unroll
;                     for (int bj = 0; bj < 2; ++bj) { float f0[8], f1[8], f2[8], fa[8], fb[8], o[8];
;                         unpack_u8(g0[bj], f0); unpack_u8(g1[bj], f1); unpack_u8(g2[bj], f2); unpack8(a[bj], fa); unpack8(b[bj], fb);
;                         const f32x4 v0 = acc[ai][bj][m][0], v1 = acc[ai][bj][m][1];
; #pragma unroll
;                         for (int j = 0; j < 4; ++j) { o[j] = f0[j] * fa[j] + f1[j] * fb[j] + f2[j] * v0[j]; o[4 + j] = f0[4 + j] * fa[4 + j] + f1[4 + j] * fb[4 + j] + f2[4 + j] * v1[j]; }
;                         *(u32x4*)(H + po + bj * HALF) = pack8(o); } }
	v_mul_f32_e32 v157, v152, v155
	v_fmac_f32_e32 v157, v153, v156
	v_fma_f32 v105, v154, v105, v157
	v_cvt_f32_ubyte0_e32 v152, v131
	v_cvt_f32_ubyte0_e32 v153, v133
	v_cvt_f32_ubyte0_e32 v154, v135
	v_lshlrev_b32_e32 v155, 16, v166
	v_lshlrev_b32_e32 v156, 16, v170
	v_mul_f32_e32 v152, 0x3b808081, v152
	v_mul_f32_e32 v153, 0x3b808081, v153
	v_mul_f32_e32 v154, 0x3b808081, v154
	v_mul_f32_e32 v157, v152, v155
	v_fmac_f32_e32 v157, v153, v156
	v_fma_f32 v98, v154, v98, v157
	v_cvt_f32_ubyte1_e32 v152, v131
	v_cvt_f32_ubyte1_e32 v153, v133
	v_cvt_f32_ubyte1_e32 v154, v135
	v_and_b32_e32 v155, 0xffff0000, v166
	v_and_b32_e32 v156, 0xffff0000, v170
	v_mul_f32_e32 v152, 0x3b808081, v152
	v_mul_f32_e32 v153, 0x3b808081, v153
	v_mul_f32_e32 v154, 0x3b808081, v154
	v_mul_f32_e32 v157, v152, v155
	v_fmac_f32_e32 v157, v153, v156
	v_fma_f32 v99, v154, v99, v157
	v_cvt_f32_ubyte2_e32 v152, v131
	v_cvt_f32_ubyte2_e32 v153, v133
	v_cvt_f32_ubyte2_e32 v154, v135
	v_lshlrev_b32_e32 v155, 16, v167
	v_lshlrev_b32_e32 v156, 16, v171
	v_mul_f32_e32 v152, 0x3b808081, v152
	v_mul_f32_e32 v153, 0x3b808081, v153
	v_mul_f32_e32 v154, 0x3b808081, v154
	v_mul_f32_e32 v157, v152, v155
	v_fmac_f32_e32 v157, v153, v156
	v_fma_f32 v100, v154, v100, v157
	v_cvt_f32_ubyte3_e32 v152, v131
	v_cvt_f32_ubyte3_e32 v153, v133
	v_cvt_f32_ubyte3_e32 v154, v135
	v_and_b32_e32 v155, 0xffff0000, v167
	v_and_b32_e32 v156, 0xffff0000, v171
	v_mul_f32_e32 v152, 0x3b808081, v152
	v_mul_f32_e32 v153, 0x3b808081, v153
	v_mul_f32_e32 v154, 0x3b808081, v154
	v_mul_f32_e32 v157, v152, v155
	v_fmac_f32_e32 v157, v153, v156
	v_fma_f32 v101, v154, v101, v157
	v_cvt_pk_bf16_f32 v102, v102, v103
	v_cvt_pk_bf16_f32 v103, v104, v105
	v_cvt_pk_bf16_f32 v104, v98, v99
	v_cvt_pk_bf16_f32 v105, v100, v101
	global_store_dwordx4 v149, v[102:105], s[62:63]
	s_waitcnt lgkmcnt(0)
	v_cvt_f32_ubyte0_e32 v152, v136
	v_cvt_f32_ubyte0_e32 v153, v160
	v_cvt_f32_ubyte0_e32 v154, v162
	v_lshlrev_b32_e32 v155, 16, v172
	v_lshlrev_b32_e32 v156, 16, v176
	v_mul_f32_e32 v152, 0x3b808081, v152
	v_mul_f32_e32 v153, 0x3b808081, v153
	v_mul_f32_e32 v154, 0x3b808081, v154
	v_mul_f32_e32 v157, v152, v155
	v_fmac_f32_e32 v157, v153, v156
	v_fma_f32 v78, v154, v78, v157
	v_cvt_f32_ubyte1_e32 v152, v136
	v_cvt_f32_ubyte1_e32 v153, v160
	v_cvt_f32_ubyte1_e32 v154, v162
	v_and_b32_e32 v155, 0xffff0000, v172
	v_and_b32_e32 v156, 0xffff0000, v176
	v_mul_f32_e32 v152, 0x3b808081, v152
	v_mul_f32_e32 v153, 0x3b808081, v153
	v_mul_f32_e32 v154, 0x3b808081, v154
	v_mul_f32_e32 v157, v152, v155
	v_fmac_f32_e32 v157, v153, v156
	v_fma_f32 v79, v154, v79, v157
	v_cvt_f32_ubyte2_e32 v152, v136
	v_cvt_f32_ubyte2_e32 v153, v160
	v_cvt_f32_ubyte2_e32 v154, v162
	v_lshlrev_b32_e32 v155, 16, v173
	v_lshlrev_b32_e32 v156, 16, v177
	v_mul_f32_e32 v152, 0x3b808081, v152
	v_mul_f32_e32 v153, 0x3b808081, v153
	v_mul_f32_e32 v154, 0x3b808081, v154
	v_mul_f32_e32 v157, v152, v155
	v_fmac_f32_e32 v157, v153, v156
	v_fma_f32 v80, v154, v80, v157
	v_cvt_f32_ubyte3_e32 v152, v136
	v_cvt_f32_ubyte3_e32 v153, v160
	v_cvt_f32_ubyte3_e32 v154, v162
	v_and_b32_e32 v155, 0xffff0000, v173
	v_and_b32_e32 v156, 0xffff0000, v177
	v_mul_f32_e32 v152, 0x3b808081, v152
	v_mul_f32_e32 v153, 0x3b808081, v153
	v_mul_f32_e32 v154, 0x3b808081, v154
	v_mul_f32_e32 v157, v152, v155
	v_fmac_f32_e32 v157, v153, v156
	v_fma_f32 v81, v154, v81, v157
	v_cvt_f32_ubyte0_e32 v152, v137
	v_cvt_f32_ubyte0_e32 v153, v161
	v_cvt_f32_ubyte0_e32 v154, v163
	v_lshlrev_b32_e32 v155, 16, v174
	v_lshlrev_b32_e32 v156, 16, v178
	v_mul_f32_e32 v152, 0x3b808081, v152
	v_mul_f32_e32 v153, 0x3b808081, v153
	v_mul_f32_e32 v154, 0x3b808081, v154
	v_mul_f32_e32 v157, v152, v155
	v_fmac_f32_e32 v157, v153, v156
	v_fma_f32 v74, v154, v74, v157
	v_cvt_f32_ubyte1_e32 v152, v137
	v_cvt_f32_ubyte1_e32 v153, v161
	v_cvt_f32_ubyte1_e32 v154, v163
	v_and_b32_e32 v155, 0xffff0000, v174
	v_and_b32_e32 v156, 0xffff0000, v178
	v_mul_f32_e32 v152, 0x3b808081, v152
	v_mul_f32_e32 v153, 0x3b808081, v153
	v_mul_f32_e32 v154, 0x3b808081, v154
	v_mul_f32_e32 v157, v152, v155
	v_fmac_f32_e32 v157, v153, v156
	v_fma_f32 v75, v154, v75, v157
	v_cvt_f32_ubyte2_e32 v152, v137
	v_cvt_f32_ubyte2_e32 v153, v161
	v_cvt_f32_ubyte2_e32 v154, v163
	v_lshlrev_b32_e32 v155, 16, v175
	v_lshlrev_b32_e32 v156, 16, v179
	v_mul_f32_e32 v152, 0x3b808081, v152
	v_mul_f32_e32 v153, 0x3b808081, v153
	v_mul_f32_e32 v154, 0x3b808081, v154
	v_mul_f32_e32 v157, v152, v155
	v_fmac_f32_e32 v157, v153, v156
	v_fma_f32 v76, v154, v76, v157
	v_cvt_f32_ubyte3_e32 v152, v137
	v_cvt_f32_ubyte3_e32 v153, v161
	v_cvt_f32_ubyte3_e32 v154, v163
	v_and_b32_e32 v155, 0xffff0000, v175
	v_and_b32_e32 v156, 0xffff0000, v179
	v_mul_f32_e32 v152, 0x3b808081, v152
	v_mul_f32_e32 v153, 0x3b808081, v153
	v_mul_f32_e32 v154, 0x3b808081, v154
	v_mul_f32_e32 v157, v152, v155
	v_fmac_f32_e32 v157, v153, v156
	v_fma_f32 v77, v154, v77, v157
	v_cvt_pk_bf16_f32 v78, v78, v79
	v_cvt_pk_bf16_f32 v79, v80, v81
	v_cvt_pk_bf16_f32 v80, v74, v75
	v_cvt_pk_bf16_f32 v81, v76, v77
	global_store_dwordx4 v149, v[78:81], s[62:63] offset:256
	v_add_u32_e32 v147, 0x80000, v145
	v_add_u32_e32 v148, 0x410000, v146
	global_load_dwordx2 v[130:131], v148, s[20:21] offset:-2048
	global_load_dwordx2 v[132:133], v148, s[20:21]
	global_load_dwordx2 v[134:135], v148, s[20:21] offset:2048
	global_load_dwordx2 v[136:137], v148, s[20:21] offset:-1920
	global_load_dwordx2 v[160:161], v148, s[20:21] offset:128
	global_load_dwordx2 v[162:163], v148, s[20:21] offset:2176
	global_load_dwordx4 v[164:167], v147, s[58:59]
	global_load_dwordx4 v[168:171], v147, s[60:61]
	global_load_dwordx4 v[172:175], v147, s[58:59] offset:256
	global_load_dwordx4 v[176:179], v147, s[60:61] offset:256
	ds_write_b128 v251, v[86:89]
	ds_read_b128 v[86:89], v252
	ds_write_b128 v251, v[82:85]
	ds_read_b128 v[82:85], v252
	ds_write_b128 v251, v[70:73]
	ds_read_b128 v[70:73], v252
	ds_write_b128 v251, v[66:69]
	ds_read_b128 v[66:69], v252
	v_add_u32_e32 v149, 0x30000, v145
	s_waitcnt vmcnt(12)
; __device__ __forceinline__ void unpack8(const u32x4 w, float* f) { f[0] = bflo(w.x); f[1] = bfhi(w.x); f[2] = bflo(w.y); f[3] = bfhi(w.y); f[4] = bflo(w.z); f[5] = bfhi(w.z); f[6] = bflo(w.w); f[7] = bfhi(w.w); }
; __device__ __forceinline__ u32x4 pack8(const float* f) { u32x4 w; w.x = cvt_pk(f[0], f[1]); w.y = cvt_pk(f[2], f[3]); w.z = cvt_pk(f[4], f[5]); w.w = cvt_pk(f[6], f[7]); return w; }
;     __device__ __forceinline__ void operator()(const f32x4 (&acc)[2][2][4][2], const UnitD& u, int wr, int wc, int fr, int fq) const {
;     ...
;             for (int ai = 0; ai < 2; ++ai)
; #pragma unroll
;                 for (int m = 0; m < 4; ++m) { const int row = row0 + ai * HALF + m * 16;
;                     const unsigned char* gp = (const unsigned char*)(proj + (size_t)row * NP + C_G) + col0; const size_t po = (size_t)row * 2048 + col0;
;                     u32x2 g0[2], g1[2], g2[2]; u32x4 a[2], b[2];
; #pragma unroll
;                     for (int bj = 0; bj < 2; ++bj) { g0[bj] = *(const u32x2*)(gp + bj * HALF); g1[bj] = *(const u32x2*)(gp + 2048 + bj * HALF); g2[bj] = *(const u32x2*)(gp + 4096 + bj * HALF);
;                         a[bj] = *(const u32x4*)(PA + po + bj * HALF); b[bj] = *(const u32x4*)(PB + po + bj * HALF); }
; #pragma unroll
;                     for (int bj = 0; bj < 2; ++bj) { float f0[8], f1[8], f2[8], fa[8], fb[8], o[8];
;                         unpack_u8(g0[bj], f0); unpack_u8(g1[bj], f1); unpack_u8(g2[bj], f2); unpack8(a[bj], fa); unpack8(b[bj], fb);
;                         const f32x4 v0 = acc[ai][bj][m][0], v1 = acc[ai][bj][m][1];
; #pragma unroll
;                         for (int j = 0; j < 4; ++j) { o[j] = f0[j] * fa[j] + f1[j] * fb[j] + f2[j] * v0[j]; o[4 + j] = f0[4 + j] * fa[4 + j] + f1[4 + j] * fb[4 + j] + f2[4 + j] * v1[j]; }
;                         *(u32x4*)(H + po + bj * HALF) = pack8(o); } }
	s_waitcnt lgkmcnt(4)
	v_cvt_f32_ubyte0_e32 v152, v198
	v_cvt_f32_ubyte0_e32 v153, v200
	v_cvt_f32_ubyte0_e32 v154, v202
	v_lshlrev_b32_e32 v155, 16, v210
	v_lshlrev_b32_e32 v156, 16, v214
	v_mul_f32_e32 v152, 0x3b808081, v152
	v_mul_f32_e32 v153, 0x3b808081, v153
	v_mul_f32_e32 v154, 0x3b808081, v154
	v_mul_f32_e32 v157, v152, v155
	v_fmac_f32_e32 v157, v153, v156
	v_fma_f32 v86, v154, v86, v157
	v_cvt_f32_ubyte1_e32 v152, v198
	v_cvt_f32_ubyte1_e32 v153, v200
	v_cvt_f32_ubyte1_e32 v154, v202
	v_and_b32_e32 v155, 0xffff0000, v210
	v_and_b32_e32 v156, 0xffff0000, v214
	v_mul_f32_e32 v152, 0x3b808081, v152
	v_mul_f32_e32 v153, 0x3b808081, v153
	v_mul_f32_e32 v154, 0x3b808081, v154
	v_mul_f32_e32 v157, v152, v155
	v_fmac_f32_e32 v157, v153, v156
	v_fma_f32 v87, v154, v87, v157
	v_cvt_f32_ubyte2_e32 v152, v198
	v_cvt_f32_ubyte2_e32 v153, v200
	v_cvt_f32_ubyte2_e32 v154, v202
	v_lshlrev_b32_e32 v155, 16, v211
	v_lshlrev_b32_e32 v156, 16, v215
	v_mul_f32_e32 v152, 0x3b808081, v152
	v_mul_f32_e32 v153, 0x3b808081, v153
	v_mul_f32_e32 v154, 0x3b808081, v154
	v_mul_f32_e32 v157, v152, v155
	v_fmac_f32_e32 v157, v153, v156
	v_fma_f32 v88, v154, v88, v157
	v_cvt_f32_ubyte3_e32 v152, v198
	v_cvt_f32_ubyte3_e32 v153, v200
	v_cvt_f32_ubyte3_e32 v154, v202
	v_and_b32_e32 v155, 0xffff0000, v211
	v_and_b32_e32 v156, 0xffff0000, v215
	v_mul_f32_e32 v152, 0x3b808081, v152
	v_mul_f32_e32 v153, 0x3b808081, v153
	v_mul_f32_e32 v154, 0x3b808081, v154
	v_mul_f32_e32 v157, v152, v155
	v_fmac_f32_e32 v157, v153, v156
	v_fma_f32 v89, v154, v89, v157
	v_cvt_f32_ubyte0_e32 v152, v199
	v_cvt_f32_ubyte0_e32 v153, v201
	v_cvt_f32_ubyte0_e32 v154, v203
	v_lshlrev_b32_e32 v155, 16, v212
	v_lshlrev_b32_e32 v156, 16, v216
	v_mul_f32_e32 v152, 0x3b808081, v152
	v_mul_f32_e32 v153, 0x3b808081, v153
	v_mul_f32_e32 v154, 0x3b808081, v154
	v_mul_f32_e32 v157, v152, v155
	v_fmac_f32_e32 v157, v153, v156
	v_fma_f32 v82, v154, v82, v157
	v_cvt_f32_ubyte1_e32 v152, v199
	v_cvt_f32_ubyte1_e32 v153, v201
	v_cvt_f32_ubyte1_e32 v154, v203
	v_and_b32_e32 v155, 0xffff0000, v212
	v_and_b32_e32 v156, 0xffff0000, v216
	v_mul_f32_e32 v152, 0x3b808081, v152
	v_mul_f32_e32 v153, 0x3b808081, v153
	v_mul_f32_e32 v154, 0x3b808081, v154
	v_mul_f32_e32 v157, v152, v155
	v_fmac_f32_e32 v157, v153, v156
	v_fma_f32 v83, v154, v83, v157
	v_cvt_f32_ubyte2_e32 v152, v199
	v_cvt_f32_ubyte2_e32 v153, v201
	v_cvt_f32_ubyte2_e32 v154, v203
	v_lshlrev_b32_e32 v155, 16, v213
	v_lshlrev_b32_e32 v156, 16, v217
	v_mul_f32_e32 v152, 0x3b808081, v152
	v_mul_f32_e32 v153, 0x3b808081, v153
	v_mul_f32_e32 v154, 0x3b808081, v154
	v_mul_f32_e32 v157, v152, v155
	v_fmac_f32_e32 v157, v153, v156
	v_fma_f32 v84, v154, v84, v157
	v_cvt_f32_ubyte3_e32 v152, v199
	v_cvt_f32_ubyte3_e32 v153, v201
	v_cvt_f32_ubyte3_e32 v154, v203
	v_and_b32_e32 v155, 0xffff0000, v213
	v_and_b32_e32 v156, 0xffff0000, v217
	v_mul_f32_e32 v152, 0x3b808081, v152
	v_mul_f32_e32 v153, 0x3b808081, v153
	v_mul_f32_e32 v154, 0x3b808081, v154
	v_mul_f32_e32 v157, v152, v155
	v_fmac_f32_e32 v157, v153, v156
	v_fma_f32 v85, v154, v85, v157
	v_cvt_pk_bf16_f32 v86, v86, v87
	v_cvt_pk_bf16_f32 v87, v88, v89
	v_cvt_pk_bf16_f32 v88, v82, v83
	v_cvt_pk_bf16_f32 v89, v84, v85
	global_store_dwordx4 v149, v[86:89], s[62:63]
	s_waitcnt lgkmcnt(0)
	v_cvt_f32_ubyte0_e32 v152, v204
	v_cvt_f32_ubyte0_e32 v153, v206
	v_cvt_f32_ubyte0_e32 v154, v208
	v_lshlrev_b32_e32 v155, 16, v218
	v_lshlrev_b32_e32 v156, 16, v222
	v_mul_f32_e32 v152, 0x3b808081, v152
	v_mul_f32_e32 v153, 0x3b808081, v153
	v_mul_f32_e32 v154, 0x3b808081, v154
	v_mul_f32_e32 v157, v152, v155
	v_fmac_f32_e32 v157, v153, v156
	v_fma_f32 v70, v154, v70, v157
	v_cvt_f32_ubyte1_e32 v152, v204
	v_cvt_f32_ubyte1_e32 v153, v206
	v_cvt_f32_ubyte1_e32 v154, v208
	v_and_b32_e32 v155, 0xffff0000, v218
	v_and_b32_e32 v156, 0xffff0000, v222
	v_mul_f32_e32 v152, 0x3b808081, v152
	v_mul_f32_e32 v153, 0x3b808081, v153
	v_mul_f32_e32 v154, 0x3b808081, v154
	v_mul_f32_e32 v157, v152, v155
	v_fmac_f32_e32 v157, v153, v156
	v_fma_f32 v71, v154, v71, v157
	v_cvt_f32_ubyte2_e32 v152, v204
	v_cvt_f32_ubyte2_e32 v153, v206
	v_cvt_f32_ubyte2_e32 v154, v208
	v_lshlrev_b32_e32 v155, 16, v219
	v_lshlrev_b32_e32 v156, 16, v223
	v_mul_f32_e32 v152, 0x3b808081, v152
	v_mul_f32_e32 v153, 0x3b808081, v153
	v_mul_f32_e32 v154, 0x3b808081, v154
	v_mul_f32_e32 v157, v152, v155
	v_fmac_f32_e32 v157, v153, v156
	v_fma_f32 v72, v154, v72, v157
	v_cvt_f32_ubyte3_e32 v152, v204
	v_cvt_f32_ubyte3_e32 v153, v206
	v_cvt_f32_ubyte3_e32 v154, v208
	v_and_b32_e32 v155, 0xffff0000, v219
	v_and_b32_e32 v156, 0xffff0000, v223
	v_mul_f32_e32 v152, 0x3b808081, v152
	v_mul_f32_e32 v153, 0x3b808081, v153
	v_mul_f32_e32 v154, 0x3b808081, v154
	v_mul_f32_e32 v157, v152, v155
	v_fmac_f32_e32 v157, v153, v156
	v_fma_f32 v73, v154, v73, v157
	v_cvt_f32_ubyte0_e32 v152, v205
	v_cvt_f32_ubyte0_e32 v153, v207
	v_cvt_f32_ubyte0_e32 v154, v209
	v_lshlrev_b32_e32 v155, 16, v220
	v_lshlrev_b32_e32 v156, 16, v224
	v_mul_f32_e32 v152, 0x3b808081, v152
	v_mul_f32_e32 v153, 0x3b808081, v153
	v_mul_f32_e32 v154, 0x3b808081, v154
	v_mul_f32_e32 v157, v152, v155
	v_fmac_f32_e32 v157, v153, v156
	v_fma_f32 v66, v154, v66, v157
	v_cvt_f32_ubyte1_e32 v152, v205
	v_cvt_f32_ubyte1_e32 v153, v207
	v_cvt_f32_ubyte1_e32 v154, v209
	v_and_b32_e32 v155, 0xffff0000, v220
	v_and_b32_e32 v156, 0xffff0000, v224
	v_mul_f32_e32 v152, 0x3b808081, v152
	v_mul_f32_e32 v153, 0x3b808081, v153
	v_mul_f32_e32 v154, 0x3b808081, v154
	v_mul_f32_e32 v157, v152, v155
	v_fmac_f32_e32 v157, v153, v156
	v_fma_f32 v67, v154, v67, v157
	v_cvt_f32_ubyte2_e32 v152, v205
	v_cvt_f32_ubyte2_e32 v153, v207
; __device__ __forceinline__ void unpack8(const u32x4 w, float* f) { f[0] = bflo(w.x); f[1] = bfhi(w.x); f[2] = bflo(w.y); f[3] = bfhi(w.y); f[4] = bflo(w.z); f[5] = bfhi(w.z); f[6] = bflo(w.w); f[7] = bfhi(w.w); }
; __device__ __forceinline__ u32x4 pack8(const float* f) { u32x4 w; w.x = cvt_pk(f[0], f[1]); w.y = cvt_pk(f[2], f[3]); w.z = cvt_pk(f[4], f[5]); w.w = cvt_pk(f[6], f[7]); return w; }
;     __device__ __forceinline__ void operator()(const f32x4 (&acc)[2][2][4][2], const UnitD& u, int wr, int wc, int fr, int fq) const {
;     ...
;             for (int ai = 0; ai < 2; ++ai)
; #pragma unroll
;                 for (int m = 0; m < 4; ++m) { const int row = row0 + ai * HALF + m * 16;
;                     const unsigned char* gp = (const unsigned char*)(proj + (size_t)row * NP + C_G) + col0; const size_t po = (size_t)row * 2048 + col0;
;                     u32x2 g0[2], g1[2], g2[2]; u32x4 a[2], b[2];
; #pragma unroll
;                     for (int bj = 0; bj < 2; ++bj) { g0[bj] = *(const u32x2*)(gp + bj * HALF); g1[bj] = *(const u32x2*)(gp + 2048 + bj * HALF); g2[bj] = *(const u32x2*)(gp + 4096 + bj * HALF);
;                         a[bj] = *(const u32x4*)(PA + po + bj * HALF); b[bj] = *(const u32x4*)(PB + po + bj * HALF); }
; #pragma unroll
;                     for (int bj = 0; bj < 2; ++bj) { float f0[8], f1[8], f2[8], fa[8], fb[8], o[8];
;                         unpack_u8(g0[bj], f0); unpack_u8(g1[bj], f1); unpack_u8(g2[bj], f2); unpack8(a[bj], fa); unpack8(b[bj], fb);
;                         const f32x4 v0 = acc[ai][bj][m][0], v1 = acc[ai][bj][m][1];
; #pragma unroll
;                         for (int j = 0; j < 4; ++j) { o[j] = f0[j] * fa[j] + f1[j] * fb[j] + f2[j] * v0[j]; o[4 + j] = f0[4 + j] * fa[4 + j] + f1[4 + j] * fb[4 + j] + f2[4 + j] * v1[j]; }
;                         *(u32x4*)(H + po + bj * HALF) = pack8(o); } }
	v_cvt_f32_ubyte2_e32 v154, v209
	v_lshlrev_b32_e32 v155, 16, v221
	v_lshlrev_b32_e32 v156, 16, v225
	v_mul_f32_e32 v152, 0x3b808081, v152
	v_mul_f32_e32 v153, 0x3b808081, v153
	v_mul_f32_e32 v154, 0x3b808081, v154
	v_mul_f32_e32 v157, v152, v155
	v_fmac_f32_e32 v157, v153, v156
	v_fma_f32 v68, v154, v68, v157
	v_cvt_f32_ubyte3_e32 v152, v205
	v_cvt_f32_ubyte3_e32 v153, v207
	v_cvt_f32_ubyte3_e32 v154, v209
	v_and_b32_e32 v155, 0xffff0000, v221
	v_and_b32_e32 v156, 0xffff0000, v225
	v_mul_f32_e32 v152, 0x3b808081, v152
	v_mul_f32_e32 v153, 0x3b808081, v153
	v_mul_f32_e32 v154, 0x3b808081, v154
	v_mul_f32_e32 v157, v152, v155
	v_fmac_f32_e32 v157, v153, v156
	v_fma_f32 v69, v154, v69, v157
	v_cvt_pk_bf16_f32 v70, v70, v71
	v_cvt_pk_bf16_f32 v71, v72, v73
	v_cvt_pk_bf16_f32 v72, v66, v67
	v_cvt_pk_bf16_f32 v73, v68, v69
	global_store_dwordx4 v149, v[70:73], s[62:63] offset:256
	v_add_u32_e32 v147, 0x90000, v145
	v_add_u32_e32 v148, 0x492000, v146
	global_load_dwordx2 v[198:199], v148, s[20:21] offset:-2048
	global_load_dwordx2 v[200:201], v148, s[20:21]
	global_load_dwordx2 v[202:203], v148, s[20:21] offset:2048
	global_load_dwordx2 v[204:205], v148, s[20:21] offset:-1920
	global_load_dwordx2 v[206:207], v148, s[20:21] offset:128
	global_load_dwordx2 v[208:209], v148, s[20:21] offset:2176
	global_load_dwordx4 v[210:213], v147, s[58:59]
	global_load_dwordx4 v[214:217], v147, s[60:61]
	global_load_dwordx4 v[218:221], v147, s[58:59] offset:256
	global_load_dwordx4 v[222:225], v147, s[60:61] offset:256
	ds_write_b128 v251, v[62:65]
	ds_read_b128 v[62:65], v252
	ds_write_b128 v251, v[58:61]
	ds_read_b128 v[58:61], v252
	ds_write_b128 v251, v[46:49]
	ds_read_b128 v[46:49], v252
	ds_write_b128 v251, v[42:45]
	ds_read_b128 v[42:45], v252
	v_add_u32_e32 v149, 0x80000, v145
	s_waitcnt vmcnt(12)
	s_waitcnt lgkmcnt(4)
	v_cvt_f32_ubyte0_e32 v152, v130
	v_cvt_f32_ubyte0_e32 v153, v132
	v_cvt_f32_ubyte0_e32 v154, v134
	v_lshlrev_b32_e32 v155, 16, v164
	v_lshlrev_b32_e32 v156, 16, v168
	v_mul_f32_e32 v152, 0x3b808081, v152
	v_mul_f32_e32 v153, 0x3b808081, v153
	v_mul_f32_e32 v154, 0x3b808081, v154
	v_mul_f32_e32 v157, v152, v155
	v_fmac_f32_e32 v157, v153, v156
	v_fma_f32 v62, v154, v62, v157
	v_cvt_f32_ubyte1_e32 v152, v130
	v_cvt_f32_ubyte1_e32 v153, v132
	v_cvt_f32_ubyte1_e32 v154, v134
	v_and_b32_e32 v155, 0xffff0000, v164
	v_and_b32_e32 v156, 0xffff0000, v168
	v_mul_f32_e32 v152, 0x3b808081, v152
	v_mul_f32_e32 v153, 0x3b808081, v153
	v_mul_f32_e32 v154, 0x3b808081, v154
	v_mul_f32_e32 v157, v152, v155
	v_fmac_f32_e32 v157, v153, v156
	v_fma_f32 v63, v154, v63, v157
	v_cvt_f32_ubyte2_e32 v152, v130
	v_cvt_f32_ubyte2_e32 v153, v132
	v_cvt_f32_ubyte2_e32 v154, v134
	v_lshlrev_b32_e32 v155, 16, v165
	v_lshlrev_b32_e32 v156, 16, v169
	v_mul_f32_e32 v152, 0x3b808081, v152
	v_mul_f32_e32 v153, 0x3b808081, v153
	v_mul_f32_e32 v154, 0x3b808081, v154
	v_mul_f32_e32 v157, v152, v155
	v_fmac_f32_e32 v157, v153, v156
	v_fma_f32 v64, v154, v64, v157
	v_cvt_f32_ubyte3_e32 v152, v130
	v_cvt_f32_ubyte3_e32 v153, v132
	v_cvt_f32_ubyte3_e32 v154, v134
	v_and_b32_e32 v155, 0xffff0000, v165
	v_and_b32_e32 v156, 0xffff0000, v169
	v_mul_f32_e32 v152, 0x3b808081, v152
	v_mul_f32_e32 v153, 0x3b808081, v153
	v_mul_f32_e32 v154, 0x3b808081, v154
	v_mul_f32_e32 v157, v152, v155
	v_fmac_f32_e32 v157, v153, v156
	v_fma_f32 v65, v154, v65, v157
	v_cvt_f32_ubyte0_e32 v152, v131
	v_cvt_f32_ubyte0_e32 v153, v133
	v_cvt_f32_ubyte0_e32 v154, v135
	v_lshlrev_b32_e32 v155, 16, v166
	v_lshlrev_b32_e32 v156, 16, v170
	v_mul_f32_e32 v152, 0x3b808081, v152
	v_mul_f32_e32 v153, 0x3b808081, v153
	v_mul_f32_e32 v154, 0x3b808081, v154
	v_mul_f32_e32 v157, v152, v155
	v_fmac_f32_e32 v157, v153, v156
	v_fma_f32 v58, v154, v58, v157
	v_cvt_f32_ubyte1_e32 v152, v131
	v_cvt_f32_ubyte1_e32 v153, v133
	v_cvt_f32_ubyte1_e32 v154, v135
	v_and_b32_e32 v155, 0xffff0000, v166
	v_and_b32_e32 v156, 0xffff0000, v170
	v_mul_f32_e32 v152, 0x3b808081, v152
	v_mul_f32_e32 v153, 0x3b808081, v153
	v_mul_f32_e32 v154, 0x3b808081, v154
	v_mul_f32_e32 v157, v152, v155
	v_fmac_f32_e32 v157, v153, v156
	v_fma_f32 v59, v154, v59, v157
	v_cvt_f32_ubyte2_e32 v152, v131
	v_cvt_f32_ubyte2_e32 v153, v133
	v_cvt_f32_ubyte2_e32 v154, v135
	v_lshlrev_b32_e32 v155, 16, v167
	v_lshlrev_b32_e32 v156, 16, v171
	v_mul_f32_e32 v152, 0x3b808081, v152
	v_mul_f32_e32 v153, 0x3b808081, v153
	v_mul_f32_e32 v154, 0x3b808081, v154
	v_mul_f32_e32 v157, v152, v155
	v_fmac_f32_e32 v157, v153, v156
	v_fma_f32 v60, v154, v60, v157
	v_cvt_f32_ubyte3_e32 v152, v131
	v_cvt_f32_ubyte3_e32 v153, v133
	v_cvt_f32_ubyte3_e32 v154, v135
	v_and_b32_e32 v155, 0xffff0000, v167
	v_and_b32_e32 v156, 0xffff0000, v171
	v_mul_f32_e32 v152, 0x3b808081, v152
	v_mul_f32_e32 v153, 0x3b808081, v153
	v_mul_f32_e32 v154, 0x3b808081, v154
	v_mul_f32_e32 v157, v152, v155
	v_fmac_f32_e32 v157, v153, v156
	v_fma_f32 v61, v154, v61, v157
	v_cvt_pk_bf16_f32 v62, v62, v63
	v_cvt_pk_bf16_f32 v63, v64, v65
	v_cvt_pk_bf16_f32 v64, v58, v59
	v_cvt_pk_bf16_f32 v65, v60, v61
	global_store_dwordx4 v149, v[62:65], s[62:63]
	s_waitcnt lgkmcnt(0)
; __device__ __forceinline__ void unpack8(const u32x4 w, float* f) { f[0] = bflo(w.x); f[1] = bfhi(w.x); f[2] = bflo(w.y); f[3] = bfhi(w.y); f[4] = bflo(w.z); f[5] = bfhi(w.z); f[6] = bflo(w.w); f[7] = bfhi(w.w); }
; __device__ __forceinline__ u32x4 pack8(const float* f) { u32x4 w; w.x = cvt_pk(f[0], f[1]); w.y = cvt_pk(f[2], f[3]); w.z = cvt_pk(f[4], f[5]); w.w = cvt_pk(f[6], f[7]); return w; }
;     __device__ __forceinline__ void operator()(const f32x4 (&acc)[2][2][4][2], const UnitD& u, int wr, int wc, int fr, int fq) const {
;     ...
;             for (int ai = 0; ai < 2; ++ai)
; #pragma unroll
;                 for (int m = 0; m < 4; ++m) { const int row = row0 + ai * HALF + m * 16;
;                     const unsigned char* gp = (const unsigned char*)(proj + (size_t)row * NP + C_G) + col0; const size_t po = (size_t)row * 2048 + col0;
;                     u32x2 g0[2], g1[2], g2[2]; u32x4 a[2], b[2];
; #pragma unroll
;                     for (int bj = 0; bj < 2; ++bj) { g0[bj] = *(const u32x2*)(gp + bj * HALF); g1[bj] = *(const u32x2*)(gp + 2048 + bj * HALF); g2[bj] = *(const u32x2*)(gp + 4096 + bj * HALF);
;                         a[bj] = *(const u32x4*)(PA + po + bj * HALF); b[bj] = *(const u32x4*)(PB + po + bj * HALF); }
; #pragma unroll
;                     for (int bj = 0; bj < 2; ++bj) { float f0[8], f1[8], f2[8], fa[8], fb[8], o[8];
;                         unpack_u8(g0[bj], f0); unpack_u8(g1[bj], f1); unpack_u8(g2[bj], f2); unpack8(a[bj], fa); unpack8(b[bj], fb);
;                         const f32x4 v0 = acc[ai][bj][m][0], v1 = acc[ai][bj][m][1];
; #pragma unroll
;                         for (int j = 0; j < 4; ++j) { o[j] = f0[j] * fa[j] + f1[j] * fb[j] + f2[j] * v0[j]; o[4 + j] = f0[4 + j] * fa[4 + j] + f1[4 + j] * fb[4 + j] + f2[4 + j] * v1[j]; }
;                         *(u32x4*)(H + po + bj * HALF) = pack8(o); } }
	v_cvt_f32_ubyte0_e32 v152, v136
	v_cvt_f32_ubyte0_e32 v153, v160
	v_cvt_f32_ubyte0_e32 v154, v162
	v_lshlrev_b32_e32 v155, 16, v172
	v_lshlrev_b32_e32 v156, 16, v176
	v_mul_f32_e32 v152, 0x3b808081, v152
	v_mul_f32_e32 v153, 0x3b808081, v153
	v_mul_f32_e32 v154, 0x3b808081, v154
	v_mul_f32_e32 v157, v152, v155
	v_fmac_f32_e32 v157, v153, v156
	v_fma_f32 v46, v154, v46, v157
	v_cvt_f32_ubyte1_e32 v152, v136
	v_cvt_f32_ubyte1_e32 v153, v160
	v_cvt_f32_ubyte1_e32 v154, v162
	v_and_b32_e32 v155, 0xffff0000, v172
	v_and_b32_e32 v156, 0xffff0000, v176
	v_mul_f32_e32 v152, 0x3b808081, v152
	v_mul_f32_e32 v153, 0x3b808081, v153
	v_mul_f32_e32 v154, 0x3b808081, v154
	v_mul_f32_e32 v157, v152, v155
	v_fmac_f32_e32 v157, v153, v156
	v_fma_f32 v47, v154, v47, v157
	v_cvt_f32_ubyte2_e32 v152, v136
	v_cvt_f32_ubyte2_e32 v153, v160
	v_cvt_f32_ubyte2_e32 v154, v162
	v_lshlrev_b32_e32 v155, 16, v173
	v_lshlrev_b32_e32 v156, 16, v177
	v_mul_f32_e32 v152, 0x3b808081, v152
	v_mul_f32_e32 v153, 0x3b808081, v153
	v_mul_f32_e32 v154, 0x3b808081, v154
	v_mul_f32_e32 v157, v152, v155
	v_fmac_f32_e32 v157, v153, v156
	v_fma_f32 v48, v154, v48, v157
	v_cvt_f32_ubyte3_e32 v152, v136
	v_cvt_f32_ubyte3_e32 v153, v160
	v_cvt_f32_ubyte3_e32 v154, v162
	v_and_b32_e32 v155, 0xffff0000, v173
	v_and_b32_e32 v156, 0xffff0000, v177
	v_mul_f32_e32 v152, 0x3b808081, v152
	v_mul_f32_e32 v153, 0x3b808081, v153
	v_mul_f32_e32 v154, 0x3b808081, v154
	v_mul_f32_e32 v157, v152, v155
	v_fmac_f32_e32 v157, v153, v156
	v_fma_f32 v49, v154, v49, v157
	v_cvt_f32_ubyte0_e32 v152, v137
	v_cvt_f32_ubyte0_e32 v153, v161
	v_cvt_f32_ubyte0_e32 v154, v163
	v_lshlrev_b32_e32 v155, 16, v174
	v_lshlrev_b32_e32 v156, 16, v178
	v_mul_f32_e32 v152, 0x3b808081, v152
	v_mul_f32_e32 v153, 0x3b808081, v153
	v_mul_f32_e32 v154, 0x3b808081, v154
	v_mul_f32_e32 v157, v152, v155
	v_fmac_f32_e32 v157, v153, v156
	v_fma_f32 v42, v154, v42, v157
	v_cvt_f32_ubyte1_e32 v152, v137
	v_cvt_f32_ubyte1_e32 v153, v161
	v_cvt_f32_ubyte1_e32 v154, v163
	v_and_b32_e32 v155, 0xffff0000, v174
	v_and_b32_e32 v156, 0xffff0000, v178
	v_mul_f32_e32 v152, 0x3b808081, v152
	v_mul_f32_e32 v153, 0x3b808081, v153
	v_mul_f32_e32 v154, 0x3b808081, v154
	v_mul_f32_e32 v157, v152, v155
	v_fmac_f32_e32 v157, v153, v156
	v_fma_f32 v43, v154, v43, v157
	v_cvt_f32_ubyte2_e32 v152, v137
	v_cvt_f32_ubyte2_e32 v153, v161
	v_cvt_f32_ubyte2_e32 v154, v163
	v_lshlrev_b32_e32 v155, 16, v175
	v_lshlrev_b32_e32 v156, 16, v179
	v_mul_f32_e32 v152, 0x3b808081, v152
	v_mul_f32_e32 v153, 0x3b808081, v153
	v_mul_f32_e32 v154, 0x3b808081, v154
	v_mul_f32_e32 v157, v152, v155
	v_fmac_f32_e32 v157, v153, v156
	v_fma_f32 v44, v154, v44, v157
	v_cvt_f32_ubyte3_e32 v152, v137
	v_cvt_f32_ubyte3_e32 v153, v161
	v_cvt_f32_ubyte3_e32 v154, v163
	v_and_b32_e32 v155, 0xffff0000, v175
	v_and_b32_e32 v156, 0xffff0000, v179
	v_mul_f32_e32 v152, 0x3b808081, v152
	v_mul_f32_e32 v153, 0x3b808081, v153
	v_mul_f32_e32 v154, 0x3b808081, v154
	v_mul_f32_e32 v157, v152, v155
	v_fmac_f32_e32 v157, v153, v156
	v_fma_f32 v45, v154, v45, v157
	v_cvt_pk_bf16_f32 v46, v46, v47
	v_cvt_pk_bf16_f32 v47, v48, v49
	v_cvt_pk_bf16_f32 v48, v42, v43
	v_cvt_pk_bf16_f32 v49, v44, v45
	global_store_dwordx4 v149, v[46:49], s[62:63] offset:256
	v_add_u32_e32 v147, 0xa0000, v145
	v_add_u32_e32 v148, 0x514000, v146
	global_load_dwordx2 v[130:131], v148, s[20:21] offset:-2048
	global_load_dwordx2 v[132:133], v148, s[20:21]
	global_load_dwordx2 v[134:135], v148, s[20:21] offset:2048
	global_load_dwordx2 v[136:137], v148, s[20:21] offset:-1920
	global_load_dwordx2 v[160:161], v148, s[20:21] offset:128
	global_load_dwordx2 v[162:163], v148, s[20:21] offset:2176
	global_load_dwordx4 v[164:167], v147, s[58:59]
	global_load_dwordx4 v[168:171], v147, s[60:61]
	global_load_dwordx4 v[172:175], v147, s[58:59] offset:256
	global_load_dwordx4 v[176:179], v147, s[60:61] offset:256
	ds_write_b128 v251, v[54:57]
	ds_read_b128 v[54:57], v252
	ds_write_b128 v251, v[50:53]
	ds_read_b128 v[50:53], v252
	ds_write_b128 v251, v[30:33]
	ds_read_b128 v[30:33], v252
	ds_write_b128 v251, v[26:29]
	ds_read_b128 v[26:29], v252
	v_add_u32_e32 v149, 0x90000, v145
	s_waitcnt vmcnt(12)
	s_waitcnt lgkmcnt(4)
	v_cvt_f32_ubyte0_e32 v152, v198
	v_cvt_f32_ubyte0_e32 v153, v200
	v_cvt_f32_ubyte0_e32 v154, v202
	v_lshlrev_b32_e32 v155, 16, v210
	v_lshlrev_b32_e32 v156, 16, v214
	v_mul_f32_e32 v152, 0x3b808081, v152
	v_mul_f32_e32 v153, 0x3b808081, v153
	v_mul_f32_e32 v154, 0x3b808081, v154
	v_mul_f32_e32 v157, v152, v155
	v_fmac_f32_e32 v157, v153, v156
	v_fma_f32 v54, v154, v54, v157
	v_cvt_f32_ubyte1_e32 v152, v198
	v_cvt_f32_ubyte1_e32 v153, v200
	v_cvt_f32_ubyte1_e32 v154, v202
	v_and_b32_e32 v155, 0xffff0000, v210
	v_and_b32_e32 v156, 0xffff0000, v214
	v_mul_f32_e32 v152, 0x3b808081, v152
	v_mul_f32_e32 v153, 0x3b808081, v153
	v_mul_f32_e32 v154, 0x3b808081, v154
	v_mul_f32_e32 v157, v152, v155
	v_fmac_f32_e32 v157, v153, v156
	v_fma_f32 v55, v154, v55, v157
	v_cvt_f32_ubyte2_e32 v152, v198
	v_cvt_f32_ubyte2_e32 v153, v200
	v_cvt_f32_ubyte2_e32 v154, v202
	v_lshlrev_b32_e32 v155, 16, v211
	v_lshlrev_b32_e32 v156, 16, v215
	v_mul_f32_e32 v152, 0x3b808081, v152
	v_mul_f32_e32 v153, 0x3b808081, v153
	v_mul_f32_e32 v154, 0x3b808081, v154
	v_mul_f32_e32 v157, v152, v155
	v_fmac_f32_e32 v157, v153, v156
	v_fma_f32 v56, v154, v56, v157
	v_cvt_f32_ubyte3_e32 v152, v198
	v_cvt_f32_ubyte3_e32 v153, v200
	v_cvt_f32_ubyte3_e32 v154, v202
	v_and_b32_e32 v155, 0xffff0000, v211
	v_and_b32_e32 v156, 0xffff0000, v215
	v_mul_f32_e32 v152, 0x3b808081, v152
	v_mul_f32_e32 v153, 0x3b808081, v153
	v_mul_f32_e32 v154, 0x3b808081, v154
; __device__ __forceinline__ void unpack8(const u32x4 w, float* f) { f[0] = bflo(w.x); f[1] = bfhi(w.x); f[2] = bflo(w.y); f[3] = bfhi(w.y); f[4] = bflo(w.z); f[5] = bfhi(w.z); f[6] = bflo(w.w); f[7] = bfhi(w.w); }
; __device__ __forceinline__ u32x4 pack8(const float* f) { u32x4 w; w.x = cvt_pk(f[0], f[1]); w.y = cvt_pk(f[2], f[3]); w.z = cvt_pk(f[4], f[5]); w.w = cvt_pk(f[6], f[7]); return w; }
;     __device__ __forceinline__ void operator()(const f32x4 (&acc)[2][2][4][2], const UnitD& u, int wr, int wc, int fr, int fq) const {
;     ...
;             for (int ai = 0; ai < 2; ++ai)
; #pragma unroll
;                 for (int m = 0; m < 4; ++m) { const int row = row0 + ai * HALF + m * 16;
;                     const unsigned char* gp = (const unsigned char*)(proj + (size_t)row * NP + C_G) + col0; const size_t po = (size_t)row * 2048 + col0;
;                     u32x2 g0[2], g1[2], g2[2]; u32x4 a[2], b[2];
; #pragma unroll
;                     for (int bj = 0; bj < 2; ++bj) { g0[bj] = *(const u32x2*)(gp + bj * HALF); g1[bj] = *(const u32x2*)(gp + 2048 + bj * HALF); g2[bj] = *(const u32x2*)(gp + 4096 + bj * HALF);
;                         a[bj] = *(const u32x4*)(PA + po + bj * HALF); b[bj] = *(const u32x4*)(PB + po + bj * HALF); }
; #pragma unroll
;                     for (int bj = 0; bj < 2; ++bj) { float f0[8], f1[8], f2[8], fa[8], fb[8], o[8];
;                         unpack_u8(g0[bj], f0); unpack_u8(g1[bj], f1); unpack_u8(g2[bj], f2); unpack8(a[bj], fa); unpack8(b[bj], fb);
;                         const f32x4 v0 = acc[ai][bj][m][0], v1 = acc[ai][bj][m][1];
; #pragma unroll
;                         for (int j = 0; j < 4; ++j) { o[j] = f0[j] * fa[j] + f1[j] * fb[j] + f2[j] * v0[j]; o[4 + j] = f0[4 + j] * fa[4 + j] + f1[4 + j] * fb[4 + j] + f2[4 + j] * v1[j]; }
;                         *(u32x4*)(H + po + bj * HALF) = pack8(o); } }
	v_mul_f32_e32 v157, v152, v155
	v_fmac_f32_e32 v157, v153, v156
	v_fma_f32 v57, v154, v57, v157
	v_cvt_f32_ubyte0_e32 v152, v199
	v_cvt_f32_ubyte0_e32 v153, v201
	v_cvt_f32_ubyte0_e32 v154, v203
	v_lshlrev_b32_e32 v155, 16, v212
	v_lshlrev_b32_e32 v156, 16, v216
	v_mul_f32_e32 v152, 0x3b808081, v152
	v_mul_f32_e32 v153, 0x3b808081, v153
	v_mul_f32_e32 v154, 0x3b808081, v154
	v_mul_f32_e32 v157, v152, v155
	v_fmac_f32_e32 v157, v153, v156
	v_fma_f32 v50, v154, v50, v157
	v_cvt_f32_ubyte1_e32 v152, v199
	v_cvt_f32_ubyte1_e32 v153, v201
	v_cvt_f32_ubyte1_e32 v154, v203
	v_and_b32_e32 v155, 0xffff0000, v212
	v_and_b32_e32 v156, 0xffff0000, v216
	v_mul_f32_e32 v152, 0x3b808081, v152
	v_mul_f32_e32 v153, 0x3b808081, v153
	v_mul_f32_e32 v154, 0x3b808081, v154
	v_mul_f32_e32 v157, v152, v155
	v_fmac_f32_e32 v157, v153, v156
	v_fma_f32 v51, v154, v51, v157
	v_cvt_f32_ubyte2_e32 v152, v199
	v_cvt_f32_ubyte2_e32 v153, v201
	v_cvt_f32_ubyte2_e32 v154, v203
	v_lshlrev_b32_e32 v155, 16, v213
	v_lshlrev_b32_e32 v156, 16, v217
	v_mul_f32_e32 v152, 0x3b808081, v152
	v_mul_f32_e32 v153, 0x3b808081, v153
	v_mul_f32_e32 v154, 0x3b808081, v154
	v_mul_f32_e32 v157, v152, v155
	v_fmac_f32_e32 v157, v153, v156
	v_fma_f32 v52, v154, v52, v157
	v_cvt_f32_ubyte3_e32 v152, v199
	v_cvt_f32_ubyte3_e32 v153, v201
	v_cvt_f32_ubyte3_e32 v154, v203
	v_and_b32_e32 v155, 0xffff0000, v213
	v_and_b32_e32 v156, 0xffff0000, v217
	v_mul_f32_e32 v152, 0x3b808081, v152
	v_mul_f32_e32 v153, 0x3b808081, v153
	v_mul_f32_e32 v154, 0x3b808081, v154
	v_mul_f32_e32 v157, v152, v155
	v_fmac_f32_e32 v157, v153, v156
	v_fma_f32 v53, v154, v53, v157
	v_cvt_pk_bf16_f32 v54, v54, v55
	v_cvt_pk_bf16_f32 v55, v56, v57
	v_cvt_pk_bf16_f32 v56, v50, v51
	v_cvt_pk_bf16_f32 v57, v52, v53
	global_store_dwordx4 v149, v[54:57], s[62:63]
	s_waitcnt lgkmcnt(0)
	v_cvt_f32_ubyte0_e32 v152, v204
	v_cvt_f32_ubyte0_e32 v153, v206
	v_cvt_f32_ubyte0_e32 v154, v208
	v_lshlrev_b32_e32 v155, 16, v218
	v_lshlrev_b32_e32 v156, 16, v222
	v_mul_f32_e32 v152, 0x3b808081, v152
	v_mul_f32_e32 v153, 0x3b808081, v153
	v_mul_f32_e32 v154, 0x3b808081, v154
	v_mul_f32_e32 v157, v152, v155
	v_fmac_f32_e32 v157, v153, v156
	v_fma_f32 v30, v154, v30, v157
	v_cvt_f32_ubyte1_e32 v152, v204
	v_cvt_f32_ubyte1_e32 v153, v206
	v_cvt_f32_ubyte1_e32 v154, v208
	v_and_b32_e32 v155, 0xffff0000, v218
	v_and_b32_e32 v156, 0xffff0000, v222
	v_mul_f32_e32 v152, 0x3b808081, v152
	v_mul_f32_e32 v153, 0x3b808081, v153
	v_mul_f32_e32 v154, 0x3b808081, v154
	v_mul_f32_e32 v157, v152, v155
	v_fmac_f32_e32 v157, v153, v156
	v_fma_f32 v31, v154, v31, v157
	v_cvt_f32_ubyte2_e32 v152, v204
	v_cvt_f32_ubyte2_e32 v153, v206
	v_cvt_f32_ubyte2_e32 v154, v208
	v_lshlrev_b32_e32 v155, 16, v219
	v_lshlrev_b32_e32 v156, 16, v223
	v_mul_f32_e32 v152, 0x3b808081, v152
	v_mul_f32_e32 v153, 0x3b808081, v153
	v_mul_f32_e32 v154, 0x3b808081, v154
	v_mul_f32_e32 v157, v152, v155
	v_fmac_f32_e32 v157, v153, v156
	v_fma_f32 v32, v154, v32, v157
	v_cvt_f32_ubyte3_e32 v152, v204
	v_cvt_f32_ubyte3_e32 v153, v206
	v_cvt_f32_ubyte3_e32 v154, v208
	v_and_b32_e32 v155, 0xffff0000, v219
	v_and_b32_e32 v156, 0xffff0000, v223
	v_mul_f32_e32 v152, 0x3b808081, v152
	v_mul_f32_e32 v153, 0x3b808081, v153
	v_mul_f32_e32 v154, 0x3b808081, v154
	v_mul_f32_e32 v157, v152, v155
	v_fmac_f32_e32 v157, v153, v156
	v_fma_f32 v33, v154, v33, v157
	v_cvt_f32_ubyte0_e32 v152, v205
	v_cvt_f32_ubyte0_e32 v153, v207
	v_cvt_f32_ubyte0_e32 v154, v209
	v_lshlrev_b32_e32 v155, 16, v220
	v_lshlrev_b32_e32 v156, 16, v224
	v_mul_f32_e32 v152, 0x3b808081, v152
	v_mul_f32_e32 v153, 0x3b808081, v153
	v_mul_f32_e32 v154, 0x3b808081, v154
	v_mul_f32_e32 v157, v152, v155
	v_fmac_f32_e32 v157, v153, v156
	v_fma_f32 v26, v154, v26, v157
	v_cvt_f32_ubyte1_e32 v152, v205
	v_cvt_f32_ubyte1_e32 v153, v207
	v_cvt_f32_ubyte1_e32 v154, v209
	v_and_b32_e32 v155, 0xffff0000, v220
	v_and_b32_e32 v156, 0xffff0000, v224
	v_mul_f32_e32 v152, 0x3b808081, v152
	v_mul_f32_e32 v153, 0x3b808081, v153
	v_mul_f32_e32 v154, 0x3b808081, v154
	v_mul_f32_e32 v157, v152, v155
	v_fmac_f32_e32 v157, v153, v156
	v_fma_f32 v27, v154, v27, v157
	v_cvt_f32_ubyte2_e32 v152, v205
	v_cvt_f32_ubyte2_e32 v153, v207
	v_cvt_f32_ubyte2_e32 v154, v209
	v_lshlrev_b32_e32 v155, 16, v221
	v_lshlrev_b32_e32 v156, 16, v225
	v_mul_f32_e32 v152, 0x3b808081, v152
	v_mul_f32_e32 v153, 0x3b808081, v153
	v_mul_f32_e32 v154, 0x3b808081, v154
	v_mul_f32_e32 v157, v152, v155
	v_fmac_f32_e32 v157, v153, v156
	v_fma_f32 v28, v154, v28, v157
	v_cvt_f32_ubyte3_e32 v152, v205
	v_cvt_f32_ubyte3_e32 v153, v207
	v_cvt_f32_ubyte3_e32 v154, v209
	v_and_b32_e32 v155, 0xffff0000, v221
	v_and_b32_e32 v156, 0xffff0000, v225
	v_mul_f32_e32 v152, 0x3b808081, v152
	v_mul_f32_e32 v153, 0x3b808081, v153
	v_mul_f32_e32 v154, 0x3b808081, v154
	v_mul_f32_e32 v157, v152, v155
	v_fmac_f32_e32 v157, v153, v156
	v_fma_f32 v29, v154, v29, v157
	v_cvt_pk_bf16_f32 v30, v30, v31
	v_cvt_pk_bf16_f32 v31, v32, v33
	v_cvt_pk_bf16_f32 v32, v26, v27
	v_cvt_pk_bf16_f32 v33, v28, v29
	global_store_dwordx4 v149, v[30:33], s[62:63] offset:256
	v_add_u32_e32 v147, 0xb0000, v145
	v_add_u32_e32 v148, 0x596000, v146
	global_load_dwordx2 v[198:199], v148, s[20:21] offset:-2048
	global_load_dwordx2 v[200:201], v148, s[20:21]
	global_load_dwordx2 v[202:203], v148, s[20:21] offset:2048
	global_load_dwordx2 v[204:205], v148, s[20:21] offset:-1920
	global_load_dwordx2 v[206:207], v148, s[20:21] offset:128
	global_load_dwordx2 v[208:209], v148, s[20:21] offset:2176
	global_load_dwordx4 v[210:213], v147, s[58:59]
	global_load_dwordx4 v[214:217], v147, s[60:61]
	global_load_dwordx4 v[218:221], v147, s[58:59] offset:256
	global_load_dwordx4 v[222:225], v147, s[60:61] offset:256
	ds_write_b128 v251, v[38:41]
	ds_read_b128 v[38:41], v252
	ds_write_b128 v251, v[34:37]
	ds_read_b128 v[34:37], v252
	ds_write_b128 v251, v[14:17]
	ds_read_b128 v[14:17], v252
	ds_write_b128 v251, v[10:13]
	ds_read_b128 v[10:13], v252
	v_add_u32_e32 v149, 0xa0000, v145
	s_waitcnt vmcnt(12)
; __device__ __forceinline__ void unpack8(const u32x4 w, float* f) { f[0] = bflo(w.x); f[1] = bfhi(w.x); f[2] = bflo(w.y); f[3] = bfhi(w.y); f[4] = bflo(w.z); f[5] = bfhi(w.z); f[6] = bflo(w.w); f[7] = bfhi(w.w); }
; __device__ __forceinline__ u32x4 pack8(const float* f) { u32x4 w; w.x = cvt_pk(f[0], f[1]); w.y = cvt_pk(f[2], f[3]); w.z = cvt_pk(f[4], f[5]); w.w = cvt_pk(f[6], f[7]); return w; }
;     __device__ __forceinline__ void operator()(const f32x4 (&acc)[2][2][4][2], const UnitD& u, int wr, int wc, int fr, int fq) const {
;     ...
;             for (int ai = 0; ai < 2; ++ai)
; #pragma unroll
;                 for (int m = 0; m < 4; ++m) { const int row = row0 + ai * HALF + m * 16;
;                     const unsigned char* gp = (const unsigned char*)(proj + (size_t)row * NP + C_G) + col0; const size_t po = (size_t)row * 2048 + col0;
;                     u32x2 g0[2], g1[2], g2[2]; u32x4 a[2], b[2];
; #pragma unroll
;                     for (int bj = 0; bj < 2; ++bj) { g0[bj] = *(const u32x2*)(gp + bj * HALF); g1[bj] = *(const u32x2*)(gp + 2048 + bj * HALF); g2[bj] = *(const u32x2*)(gp + 4096 + bj * HALF);
;                         a[bj] = *(const u32x4*)(PA + po + bj * HALF); b[bj] = *(const u32x4*)(PB + po + bj * HALF); }
; #pragma unroll
;                     for (int bj = 0; bj < 2; ++bj) { float f0[8], f1[8], f2[8], fa[8], fb[8], o[8];
;                         unpack_u8(g0[bj], f0); unpack_u8(g1[bj], f1); unpack_u8(g2[bj], f2); unpack8(a[bj], fa); unpack8(b[bj], fb);
;                         const f32x4 v0 = acc[ai][bj][m][0], v1 = acc[ai][bj][m][1];
; #pragma unroll
;                         for (int j = 0; j < 4; ++j) { o[j] = f0[j] * fa[j] + f1[j] * fb[j] + f2[j] * v0[j]; o[4 + j] = f0[4 + j] * fa[4 + j] + f1[4 + j] * fb[4 + j] + f2[4 + j] * v1[j]; }
;                         *(u32x4*)(H + po + bj * HALF) = pack8(o); } }
	s_waitcnt lgkmcnt(4)
	v_cvt_f32_ubyte0_e32 v152, v130
	v_cvt_f32_ubyte0_e32 v153, v132
	v_cvt_f32_ubyte0_e32 v154, v134
	v_lshlrev_b32_e32 v155, 16, v164
	v_lshlrev_b32_e32 v156, 16, v168
	v_mul_f32_e32 v152, 0x3b808081, v152
	v_mul_f32_e32 v153, 0x3b808081, v153
	v_mul_f32_e32 v154, 0x3b808081, v154
	v_mul_f32_e32 v157, v152, v155
	v_fmac_f32_e32 v157, v153, v156
	v_fma_f32 v38, v154, v38, v157
	v_cvt_f32_ubyte1_e32 v152, v130
	v_cvt_f32_ubyte1_e32 v153, v132
	v_cvt_f32_ubyte1_e32 v154, v134
	v_and_b32_e32 v155, 0xffff0000, v164
	v_and_b32_e32 v156, 0xffff0000, v168
	v_mul_f32_e32 v152, 0x3b808081, v152
	v_mul_f32_e32 v153, 0x3b808081, v153
	v_mul_f32_e32 v154, 0x3b808081, v154
	v_mul_f32_e32 v157, v152, v155
	v_fmac_f32_e32 v157, v153, v156
	v_fma_f32 v39, v154, v39, v157
	v_cvt_f32_ubyte2_e32 v152, v130
	v_cvt_f32_ubyte2_e32 v153, v132
	v_cvt_f32_ubyte2_e32 v154, v134
	v_lshlrev_b32_e32 v155, 16, v165
	v_lshlrev_b32_e32 v156, 16, v169
	v_mul_f32_e32 v152, 0x3b808081, v152
	v_mul_f32_e32 v153, 0x3b808081, v153
	v_mul_f32_e32 v154, 0x3b808081, v154
	v_mul_f32_e32 v157, v152, v155
	v_fmac_f32_e32 v157, v153, v156
	v_fma_f32 v40, v154, v40, v157
	v_cvt_f32_ubyte3_e32 v152, v130
	v_cvt_f32_ubyte3_e32 v153, v132
	v_cvt_f32_ubyte3_e32 v154, v134
	v_and_b32_e32 v155, 0xffff0000, v165
	v_and_b32_e32 v156, 0xffff0000, v169
	v_mul_f32_e32 v152, 0x3b808081, v152
	v_mul_f32_e32 v153, 0x3b808081, v153
	v_mul_f32_e32 v154, 0x3b808081, v154
	v_mul_f32_e32 v157, v152, v155
	v_fmac_f32_e32 v157, v153, v156
	v_fma_f32 v41, v154, v41, v157
	v_cvt_f32_ubyte0_e32 v152, v131
	v_cvt_f32_ubyte0_e32 v153, v133
	v_cvt_f32_ubyte0_e32 v154, v135
	v_lshlrev_b32_e32 v155, 16, v166
	v_lshlrev_b32_e32 v156, 16, v170
	v_mul_f32_e32 v152, 0x3b808081, v152
	v_mul_f32_e32 v153, 0x3b808081, v153
	v_mul_f32_e32 v154, 0x3b808081, v154
	v_mul_f32_e32 v157, v152, v155
	v_fmac_f32_e32 v157, v153, v156
	v_fma_f32 v34, v154, v34, v157
	v_cvt_f32_ubyte1_e32 v152, v131
	v_cvt_f32_ubyte1_e32 v153, v133
	v_cvt_f32_ubyte1_e32 v154, v135
	v_and_b32_e32 v155, 0xffff0000, v166
	v_and_b32_e32 v156, 0xffff0000, v170
	v_mul_f32_e32 v152, 0x3b808081, v152
	v_mul_f32_e32 v153, 0x3b808081, v153
	v_mul_f32_e32 v154, 0x3b808081, v154
	v_mul_f32_e32 v157, v152, v155
	v_fmac_f32_e32 v157, v153, v156
	v_fma_f32 v35, v154, v35, v157
	v_cvt_f32_ubyte2_e32 v152, v131
	v_cvt_f32_ubyte2_e32 v153, v133
	v_cvt_f32_ubyte2_e32 v154, v135
	v_lshlrev_b32_e32 v155, 16, v167
	v_lshlrev_b32_e32 v156, 16, v171
	v_mul_f32_e32 v152, 0x3b808081, v152
	v_mul_f32_e32 v153, 0x3b808081, v153
	v_mul_f32_e32 v154, 0x3b808081, v154
	v_mul_f32_e32 v157, v152, v155
	v_fmac_f32_e32 v157, v153, v156
	v_fma_f32 v36, v154, v36, v157
	v_cvt_f32_ubyte3_e32 v152, v131
	v_cvt_f32_ubyte3_e32 v153, v133
	v_cvt_f32_ubyte3_e32 v154, v135
	v_and_b32_e32 v155, 0xffff0000, v167
	v_and_b32_e32 v156, 0xffff0000, v171
	v_mul_f32_e32 v152, 0x3b808081, v152
	v_mul_f32_e32 v153, 0x3b808081, v153
	v_mul_f32_e32 v154, 0x3b808081, v154
	v_mul_f32_e32 v157, v152, v155
	v_fmac_f32_e32 v157, v153, v156
	v_fma_f32 v37, v154, v37, v157
	v_cvt_pk_bf16_f32 v38, v38, v39
	v_cvt_pk_bf16_f32 v39, v40, v41
	v_cvt_pk_bf16_f32 v40, v34, v35
	v_cvt_pk_bf16_f32 v41, v36, v37
	global_store_dwordx4 v149, v[38:41], s[62:63]
	s_waitcnt lgkmcnt(0)
	v_cvt_f32_ubyte0_e32 v152, v136
	v_cvt_f32_ubyte0_e32 v153, v160
	v_cvt_f32_ubyte0_e32 v154, v162
	v_lshlrev_b32_e32 v155, 16, v172
	v_lshlrev_b32_e32 v156, 16, v176
	v_mul_f32_e32 v152, 0x3b808081, v152
	v_mul_f32_e32 v153, 0x3b808081, v153
	v_mul_f32_e32 v154, 0x3b808081, v154
	v_mul_f32_e32 v157, v152, v155
	v_fmac_f32_e32 v157, v153, v156
	v_fma_f32 v14, v154, v14, v157
	v_cvt_f32_ubyte1_e32 v152, v136
	v_cvt_f32_ubyte1_e32 v153, v160
	v_cvt_f32_ubyte1_e32 v154, v162
	v_and_b32_e32 v155, 0xffff0000, v172
	v_and_b32_e32 v156, 0xffff0000, v176
	v_mul_f32_e32 v152, 0x3b808081, v152
	v_mul_f32_e32 v153, 0x3b808081, v153
	v_mul_f32_e32 v154, 0x3b808081, v154
	v_mul_f32_e32 v157, v152, v155
	v_fmac_f32_e32 v157, v153, v156
	v_fma_f32 v15, v154, v15, v157
	v_cvt_f32_ubyte2_e32 v152, v136
	v_cvt_f32_ubyte2_e32 v153, v160
	v_cvt_f32_ubyte2_e32 v154, v162
	v_lshlrev_b32_e32 v155, 16, v173
	v_lshlrev_b32_e32 v156, 16, v177
	v_mul_f32_e32 v152, 0x3b808081, v152
	v_mul_f32_e32 v153, 0x3b808081, v153
	v_mul_f32_e32 v154, 0x3b808081, v154
	v_mul_f32_e32 v157, v152, v155
	v_fmac_f32_e32 v157, v153, v156
	v_fma_f32 v16, v154, v16, v157
	v_cvt_f32_ubyte3_e32 v152, v136
	v_cvt_f32_ubyte3_e32 v153, v160
	v_cvt_f32_ubyte3_e32 v154, v162
	v_and_b32_e32 v155, 0xffff0000, v173
	v_and_b32_e32 v156, 0xffff0000, v177
	v_mul_f32_e32 v152, 0x3b808081, v152
	v_mul_f32_e32 v153, 0x3b808081, v153
	v_mul_f32_e32 v154, 0x3b808081, v154
	v_mul_f32_e32 v157, v152, v155
	v_fmac_f32_e32 v157, v153, v156
	v_fma_f32 v17, v154, v17, v157
	v_cvt_f32_ubyte0_e32 v152, v137
	v_cvt_f32_ubyte0_e32 v153, v161
	v_cvt_f32_ubyte0_e32 v154, v163
	v_lshlrev_b32_e32 v155, 16, v174
	v_lshlrev_b32_e32 v156, 16, v178
	v_mul_f32_e32 v152, 0x3b808081, v152
	v_mul_f32_e32 v153, 0x3b808081, v153
	v_mul_f32_e32 v154, 0x3b808081, v154
	v_mul_f32_e32 v157, v152, v155
	v_fmac_f32_e32 v157, v153, v156
	v_fma_f32 v10, v154, v10, v157
	v_cvt_f32_ubyte1_e32 v152, v137
	v_cvt_f32_ubyte1_e32 v153, v161
	v_cvt_f32_ubyte1_e32 v154, v163
	v_and_b32_e32 v155, 0xffff0000, v174
	v_and_b32_e32 v156, 0xffff0000, v178
	v_mul_f32_e32 v152, 0x3b808081, v152
	v_mul_f32_e32 v153, 0x3b808081, v153
	v_mul_f32_e32 v154, 0x3b808081, v154
	v_mul_f32_e32 v157, v152, v155
	v_fmac_f32_e32 v157, v153, v156
	v_fma_f32 v11, v154, v11, v157
	v_cvt_f32_ubyte2_e32 v152, v137
	v_cvt_f32_ubyte2_e32 v153, v161
	v_cvt_f32_ubyte2_e32 v154, v163
	v_lshlrev_b32_e32 v155, 16, v175
	v_lshlrev_b32_e32 v156, 16, v179
	v_mul_f32_e32 v152, 0x3b808081, v152
	v_mul_f32_e32 v153, 0x3b808081, v153
	v_mul_f32_e32 v154, 0x3b808081, v154
	v_mul_f32_e32 v157, v152, v155
	v_fmac_f32_e32 v157, v153, v156
	v_fma_f32 v12, v154, v12, v157
	v_cvt_f32_ubyte3_e32 v152, v137
	v_cvt_f32_ubyte3_e32 v153, v161
	v_cvt_f32_ubyte3_e32 v154, v163
	v_and_b32_e32 v155, 0xffff0000, v175
	v_and_b32_e32 v156, 0xffff0000, v179
	v_mul_f32_e32 v152, 0x3b808081, v152
	v_mul_f32_e32 v153, 0x3b808081, v153
	v_mul_f32_e32 v154, 0x3b808081, v154
	v_mul_f32_e32 v157, v152, v155
	v_fmac_f32_e32 v157, v153, v156
	v_fma_f32 v13, v154, v13, v157
	v_cvt_pk_bf16_f32 v14, v14, v15
	v_cvt_pk_bf16_f32 v15, v16, v17
	v_cvt_pk_bf16_f32 v16, v10, v11
	v_cvt_pk_bf16_f32 v17, v12, v13
	global_store_dwordx4 v149, v[14:17], s[62:63] offset:256
	ds_write_b128 v251, v[22:25]
	ds_read_b128 v[22:25], v252
	ds_write_b128 v251, v[18:21]
	ds_read_b128 v[18:21], v252
	ds_write_b128 v251, v[6:9]
	ds_read_b128 v[6:9], v252
	ds_write_b128 v251, v[2:5]
	ds_read_b128 v[2:5], v252
	v_add_u32_e32 v149, 0xb0000, v145
	s_waitcnt vmcnt(2)
; __device__ __forceinline__ void unpack8(const u32x4 w, float* f) { f[0] = bflo(w.x); f[1] = bfhi(w.x); f[2] = bflo(w.y); f[3] = bfhi(w.y); f[4] = bflo(w.z); f[5] = bfhi(w.z); f[6] = bflo(w.w); f[7] = bfhi(w.w); }
; __device__ __forceinline__ u32x4 pack8(const float* f) { u32x4 w; w.x = cvt_pk(f[0], f[1]); w.y = cvt_pk(f[2], f[3]); w.z = cvt_pk(f[4], f[5]); w.w = cvt_pk(f[6], f[7]); return w; }
;     __device__ __forceinline__ void operator()(const f32x4 (&acc)[2][2][4][2], const UnitD& u, int wr, int wc, int fr, int fq) const {
;     ...
;             for (int ai = 0; ai < 2; ++ai)
; #pragma unroll
;                 for (int m = 0; m < 4; ++m) { const int row = row0 + ai * HALF + m * 16;
;                     const unsigned char* gp = (const unsigned char*)(proj + (size_t)row * NP + C_G) + col0; const size_t po = (size_t)row * 2048 + col0;
;                     u32x2 g0[2], g1[2], g2[2]; u32x4 a[2], b[2];
; #pragma unroll
;                     for (int bj = 0; bj < 2; ++bj) { g0[bj] = *(const u32x2*)(gp + bj * HALF); g1[bj] = *(const u32x2*)(gp + 2048 + bj * HALF); g2[bj] = *(const u32x2*)(gp + 4096 + bj * HALF);
;                         a[bj] = *(const u32x4*)(PA + po + bj * HALF); b[bj] = *(const u32x4*)(PB + po + bj * HALF); }
; #pragma unroll
;                     for (int bj = 0; bj < 2; ++bj) { float f0[8], f1[8], f2[8], fa[8], fb[8], o[8];
;                         unpack_u8(g0[bj], f0); unpack_u8(g1[bj], f1); unpack_u8(g2[bj], f2); unpack8(a[bj], fa); unpack8(b[bj], fb);
;                         const f32x4 v0 = acc[ai][bj][m][0], v1 = acc[ai][bj][m][1];
; #pragma unroll
;                         for (int j = 0; j < 4; ++j) { o[j] = f0[j] * fa[j] + f1[j] * fb[j] + f2[j] * v0[j]; o[4 + j] = f0[4 + j] * fa[4 + j] + f1[4 + j] * fb[4 + j] + f2[4 + j] * v1[j]; }
;                         *(u32x4*)(H + po + bj * HALF) = pack8(o); } }
	s_waitcnt lgkmcnt(4)
	v_cvt_f32_ubyte0_e32 v152, v198
	v_cvt_f32_ubyte0_e32 v153, v200
	v_cvt_f32_ubyte0_e32 v154, v202
	v_lshlrev_b32_e32 v155, 16, v210
	v_lshlrev_b32_e32 v156, 16, v214
	v_mul_f32_e32 v152, 0x3b808081, v152
	v_mul_f32_e32 v153, 0x3b808081, v153
	v_mul_f32_e32 v154, 0x3b808081, v154
	v_mul_f32_e32 v157, v152, v155
	v_fmac_f32_e32 v157, v153, v156
	v_fma_f32 v22, v154, v22, v157
	v_cvt_f32_ubyte1_e32 v152, v198
	v_cvt_f32_ubyte1_e32 v153, v200
	v_cvt_f32_ubyte1_e32 v154, v202
	v_and_b32_e32 v155, 0xffff0000, v210
	v_and_b32_e32 v156, 0xffff0000, v214
	v_mul_f32_e32 v152, 0x3b808081, v152
	v_mul_f32_e32 v153, 0x3b808081, v153
	v_mul_f32_e32 v154, 0x3b808081, v154
	v_mul_f32_e32 v157, v152, v155
	v_fmac_f32_e32 v157, v153, v156
	v_fma_f32 v23, v154, v23, v157
	v_cvt_f32_ubyte2_e32 v152, v198
	v_cvt_f32_ubyte2_e32 v153, v200
	v_cvt_f32_ubyte2_e32 v154, v202
	v_lshlrev_b32_e32 v155, 16, v211
	v_lshlrev_b32_e32 v156, 16, v215
	v_mul_f32_e32 v152, 0x3b808081, v152
	v_mul_f32_e32 v153, 0x3b808081, v153
	v_mul_f32_e32 v154, 0x3b808081, v154
	v_mul_f32_e32 v157, v152, v155
	v_fmac_f32_e32 v157, v153, v156
	v_fma_f32 v24, v154, v24, v157
	v_cvt_f32_ubyte3_e32 v152, v198
	v_cvt_f32_ubyte3_e32 v153, v200
	v_cvt_f32_ubyte3_e32 v154, v202
	v_and_b32_e32 v155, 0xffff0000, v211
	v_and_b32_e32 v156, 0xffff0000, v215
	v_mul_f32_e32 v152, 0x3b808081, v152
	v_mul_f32_e32 v153, 0x3b808081, v153
	v_mul_f32_e32 v154, 0x3b808081, v154
	v_mul_f32_e32 v157, v152, v155
	v_fmac_f32_e32 v157, v153, v156
	v_fma_f32 v25, v154, v25, v157
	v_cvt_f32_ubyte0_e32 v152, v199
	v_cvt_f32_ubyte0_e32 v153, v201
	v_cvt_f32_ubyte0_e32 v154, v203
	v_lshlrev_b32_e32 v155, 16, v212
	v_lshlrev_b32_e32 v156, 16, v216
	v_mul_f32_e32 v152, 0x3b808081, v152
	v_mul_f32_e32 v153, 0x3b808081, v153
	v_mul_f32_e32 v154, 0x3b808081, v154
	v_mul_f32_e32 v157, v152, v155
	v_fmac_f32_e32 v157, v153, v156
	v_fma_f32 v18, v154, v18, v157
	v_cvt_f32_ubyte1_e32 v152, v199
	v_cvt_f32_ubyte1_e32 v153, v201
	v_cvt_f32_ubyte1_e32 v154, v203
	v_and_b32_e32 v155, 0xffff0000, v212
	v_and_b32_e32 v156, 0xffff0000, v216
	v_mul_f32_e32 v152, 0x3b808081, v152
	v_mul_f32_e32 v153, 0x3b808081, v153
	v_mul_f32_e32 v154, 0x3b808081, v154
	v_mul_f32_e32 v157, v152, v155
	v_fmac_f32_e32 v157, v153, v156
	v_fma_f32 v19, v154, v19, v157
	v_cvt_f32_ubyte2_e32 v152, v199
	v_cvt_f32_ubyte2_e32 v153, v201
	v_cvt_f32_ubyte2_e32 v154, v203
	v_lshlrev_b32_e32 v155, 16, v213
	v_lshlrev_b32_e32 v156, 16, v217
	v_mul_f32_e32 v152, 0x3b808081, v152
	v_mul_f32_e32 v153, 0x3b808081, v153
	v_mul_f32_e32 v154, 0x3b808081, v154
	v_mul_f32_e32 v157, v152, v155
	v_fmac_f32_e32 v157, v153, v156
	v_fma_f32 v20, v154, v20, v157
	v_cvt_f32_ubyte3_e32 v152, v199
	v_cvt_f32_ubyte3_e32 v153, v201
	v_cvt_f32_ubyte3_e32 v154, v203
	v_and_b32_e32 v155, 0xffff0000, v213
	v_and_b32_e32 v156, 0xffff0000, v217
	v_mul_f32_e32 v152, 0x3b808081, v152
	v_mul_f32_e32 v153, 0x3b808081, v153
	v_mul_f32_e32 v154, 0x3b808081, v154
	v_mul_f32_e32 v157, v152, v155
	v_fmac_f32_e32 v157, v153, v156
	v_fma_f32 v21, v154, v21, v157
	v_cvt_pk_bf16_f32 v22, v22, v23
	v_cvt_pk_bf16_f32 v23, v24, v25
	v_cvt_pk_bf16_f32 v24, v18, v19
	v_cvt_pk_bf16_f32 v25, v20, v21
	global_store_dwordx4 v149, v[22:25], s[62:63]
	s_waitcnt lgkmcnt(0)
	v_cvt_f32_ubyte0_e32 v152, v204
	v_cvt_f32_ubyte0_e32 v153, v206
	v_cvt_f32_ubyte0_e32 v154, v208
	v_lshlrev_b32_e32 v155, 16, v218
	v_lshlrev_b32_e32 v156, 16, v222
	v_mul_f32_e32 v152, 0x3b808081, v152
	v_mul_f32_e32 v153, 0x3b808081, v153
	v_mul_f32_e32 v154, 0x3b808081, v154
	v_mul_f32_e32 v157, v152, v155
	v_fmac_f32_e32 v157, v153, v156
	v_fma_f32 v6, v154, v6, v157
	v_cvt_f32_ubyte1_e32 v152, v204
	v_cvt_f32_ubyte1_e32 v153, v206
	v_cvt_f32_ubyte1_e32 v154, v208
	v_and_b32_e32 v155, 0xffff0000, v218
	v_and_b32_e32 v156, 0xffff0000, v222
	v_mul_f32_e32 v152, 0x3b808081, v152
	v_mul_f32_e32 v153, 0x3b808081, v153
	v_mul_f32_e32 v154, 0x3b808081, v154
	v_mul_f32_e32 v157, v152, v155
	v_fmac_f32_e32 v157, v153, v156
	v_fma_f32 v7, v154, v7, v157
	v_cvt_f32_ubyte2_e32 v152, v204
	v_cvt_f32_ubyte2_e32 v153, v206
	v_cvt_f32_ubyte2_e32 v154, v208
	v_lshlrev_b32_e32 v155, 16, v219
	v_lshlrev_b32_e32 v156, 16, v223
	v_mul_f32_e32 v152, 0x3b808081, v152
	v_mul_f32_e32 v153, 0x3b808081, v153
	v_mul_f32_e32 v154, 0x3b808081, v154
	v_mul_f32_e32 v157, v152, v155
	v_fmac_f32_e32 v157, v153, v156
	v_fma_f32 v8, v154, v8, v157
	v_cvt_f32_ubyte3_e32 v152, v204
	v_cvt_f32_ubyte3_e32 v153, v206
	v_cvt_f32_ubyte3_e32 v154, v208
	v_and_b32_e32 v155, 0xffff0000, v219
	v_and_b32_e32 v156, 0xffff0000, v223
	v_mul_f32_e32 v152, 0x3b808081, v152
	v_mul_f32_e32 v153, 0x3b808081, v153
	v_mul_f32_e32 v154, 0x3b808081, v154
	v_mul_f32_e32 v157, v152, v155
	v_fmac_f32_e32 v157, v153, v156
	v_fma_f32 v9, v154, v9, v157
	v_cvt_f32_ubyte0_e32 v152, v205
	v_cvt_f32_ubyte0_e32 v153, v207
	v_cvt_f32_ubyte0_e32 v154, v209
	v_lshlrev_b32_e32 v155, 16, v220
	v_lshlrev_b32_e32 v156, 16, v224
	v_mul_f32_e32 v152, 0x3b808081, v152
	v_mul_f32_e32 v153, 0x3b808081, v153
	v_mul_f32_e32 v154, 0x3b808081, v154
	v_mul_f32_e32 v157, v152, v155
	v_fmac_f32_e32 v157, v153, v156
	v_fma_f32 v2, v154, v2, v157
	v_cvt_f32_ubyte1_e32 v152, v205
	v_cvt_f32_ubyte1_e32 v153, v207
	v_cvt_f32_ubyte1_e32 v154, v209
	v_and_b32_e32 v155, 0xffff0000, v220
	v_and_b32_e32 v156, 0xffff0000, v224
	v_mul_f32_e32 v152, 0x3b808081, v152
	v_mul_f32_e32 v153, 0x3b808081, v153
	v_mul_f32_e32 v154, 0x3b808081, v154
	v_mul_f32_e32 v157, v152, v155
	v_fmac_f32_e32 v157, v153, v156
	v_fma_f32 v3, v154, v3, v157
	v_cvt_f32_ubyte2_e32 v152, v205
	v_cvt_f32_ubyte2_e32 v153, v207
	v_cvt_f32_ubyte2_e32 v154, v209
	v_lshlrev_b32_e32 v155, 16, v221
	v_lshlrev_b32_e32 v156, 16, v225
	v_mul_f32_e32 v152, 0x3b808081, v152
	v_mul_f32_e32 v153, 0x3b808081, v153
	v_mul_f32_e32 v154, 0x3b808081, v154
	v_mul_f32_e32 v157, v152, v155
	v_fmac_f32_e32 v157, v153, v156
	v_fma_f32 v4, v154, v4, v157
	v_cvt_f32_ubyte3_e32 v152, v205
	v_cvt_f32_ubyte3_e32 v153, v207
	v_cvt_f32_ubyte3_e32 v154, v209
	v_and_b32_e32 v155, 0xffff0000, v221
	v_and_b32_e32 v156, 0xffff0000, v225
	v_mul_f32_e32 v152, 0x3b808081, v152
	v_mul_f32_e32 v153, 0x3b808081, v153
	v_mul_f32_e32 v154, 0x3b808081, v154
	v_mul_f32_e32 v157, v152, v155
	v_fmac_f32_e32 v157, v153, v156
	v_fma_f32 v5, v154, v5, v157
	v_cvt_pk_bf16_f32 v6, v6, v7
	v_cvt_pk_bf16_f32 v7, v8, v9
	v_cvt_pk_bf16_f32 v8, v2, v3
	v_cvt_pk_bf16_f32 v9, v4, v5
	global_store_dwordx4 v149, v[6:9], s[62:63] offset:256
	s_branch .Lg3_done
; __device__ __forceinline__ unsigned cvt_pk(float lo, float hi) { unsigned r; asm volatile("v_cvt_pk_bf16_f32 %0, %1, %2" : "=v"(r) : "v"(lo), "v"(hi)); return r; }
; #define GAS __attribute__((address_space(1)))
;     __device__ __forceinline__ void operator()(const f32x4 (&acc)[2][2][4][2], const UnitD& u, int wr, int wc, int fr, int fq) const {
;     ...
;             GAS bf16_t* C = (GAS bf16_t*)(unsigned long long)u.C;
; #pragma unroll
;             for (int ai = 0; ai < 2; ++ai)
; #pragma unroll
;                 for (int m = 0; m < 4; ++m) { GAS bf16_t* rowp = C + (size_t)(row0 + ai * HALF + m * 16) * 2048 + col0;
; #pragma unroll
;                     for (int bj = 0; bj < 2; ++bj) { const f32x4 v0 = acc[ai][bj][m][0], v1 = acc[ai][bj][m][1];
;                         u32x4 w; w.x = cvt_pk(v0[0], v0[1]); w.y = cvt_pk(v0[2], v0[3]); w.z = cvt_pk(v1[0], v1[1]); w.w = cvt_pk(v1[2], v1[3]);
;                         *(GAS u32x4*)(rowp + bj * HALF) = w; } }
.Lg3_k01:
	v_lshl_add_u32 v145, v144, 11, v150
	v_lshlrev_b32_e32 v145, 1, v145
	v_cvt_pk_bf16_f32 v126, v126, v127
	v_cvt_pk_bf16_f32 v127, v128, v129
	v_cvt_pk_bf16_f32 v128, v122, v123
	v_cvt_pk_bf16_f32 v129, v124, v125
	ds_write_b128 v251, v[126:129]
	ds_read_b128 v[126:129], v252
	v_cvt_pk_bf16_f32 v110, v110, v111
	v_cvt_pk_bf16_f32 v111, v112, v113
	v_cvt_pk_bf16_f32 v112, v106, v107
	v_cvt_pk_bf16_f32 v113, v108, v109
	ds_write_b128 v251, v[110:113]
	ds_read_b128 v[110:113], v252
	v_cvt_pk_bf16_f32 v118, v118, v119
	v_cvt_pk_bf16_f32 v119, v120, v121
	v_cvt_pk_bf16_f32 v120, v114, v115
	v_cvt_pk_bf16_f32 v121, v116, v117
	ds_write_b128 v251, v[118:121]
	ds_read_b128 v[118:121], v252
	v_mov_b32_e32 v253, v145
	s_waitcnt lgkmcnt(4)
	global_store_dwordx4 v253, v[126:129], s[16:17]
	v_cvt_pk_bf16_f32 v94, v94, v95
	v_cvt_pk_bf16_f32 v95, v96, v97
	v_cvt_pk_bf16_f32 v96, v90, v91
	v_cvt_pk_bf16_f32 v97, v92, v93
	ds_write_b128 v251, v[94:97]
	ds_read_b128 v[94:97], v252
	s_waitcnt lgkmcnt(4)
	global_store_dwordx4 v253, v[110:113], s[16:17] offset:256
	v_cvt_pk_bf16_f32 v102, v102, v103
	v_cvt_pk_bf16_f32 v103, v104, v105
	v_cvt_pk_bf16_f32 v104, v98, v99
	v_cvt_pk_bf16_f32 v105, v100, v101
	ds_write_b128 v251, v[102:105]
	ds_read_b128 v[102:105], v252
	v_add_u32_e32 v253, 0x10000, v145
	s_waitcnt lgkmcnt(4)
	global_store_dwordx4 v253, v[118:121], s[16:17]
	v_cvt_pk_bf16_f32 v78, v78, v79
	v_cvt_pk_bf16_f32 v79, v80, v81
	v_cvt_pk_bf16_f32 v80, v74, v75
	v_cvt_pk_bf16_f32 v81, v76, v77
	ds_write_b128 v251, v[78:81]
	ds_read_b128 v[78:81], v252
	s_waitcnt lgkmcnt(4)
	global_store_dwordx4 v253, v[94:97], s[16:17] offset:256
	v_cvt_pk_bf16_f32 v86, v86, v87
	v_cvt_pk_bf16_f32 v87, v88, v89
	v_cvt_pk_bf16_f32 v88, v82, v83
	v_cvt_pk_bf16_f32 v89, v84, v85
	ds_write_b128 v251, v[86:89]
	ds_read_b128 v[86:89], v252
	v_add_u32_e32 v253, 0x20000, v145
	s_waitcnt lgkmcnt(4)
	global_store_dwordx4 v253, v[102:105], s[16:17]
	v_cvt_pk_bf16_f32 v70, v70, v71
	v_cvt_pk_bf16_f32 v71, v72, v73
	v_cvt_pk_bf16_f32 v72, v66, v67
	v_cvt_pk_bf16_f32 v73, v68, v69
	ds_write_b128 v251, v[70:73]
	ds_read_b128 v[70:73], v252
	s_waitcnt lgkmcnt(4)
	global_store_dwordx4 v253, v[78:81], s[16:17] offset:256
	v_cvt_pk_bf16_f32 v62, v62, v63
	v_cvt_pk_bf16_f32 v63, v64, v65
	v_cvt_pk_bf16_f32 v64, v58, v59
	v_cvt_pk_bf16_f32 v65, v60, v61
	ds_write_b128 v251, v[62:65]
	ds_read_b128 v[62:65], v252
	v_add_u32_e32 v253, 0x30000, v145
	s_waitcnt lgkmcnt(4)
	global_store_dwordx4 v253, v[86:89], s[16:17]
	v_cvt_pk_bf16_f32 v46, v46, v47
	v_cvt_pk_bf16_f32 v47, v48, v49
	v_cvt_pk_bf16_f32 v48, v42, v43
	v_cvt_pk_bf16_f32 v49, v44, v45
	ds_write_b128 v251, v[46:49]
	ds_read_b128 v[46:49], v252
	s_waitcnt lgkmcnt(4)
	global_store_dwordx4 v253, v[70:73], s[16:17] offset:256
	v_cvt_pk_bf16_f32 v54, v54, v55
	v_cvt_pk_bf16_f32 v55, v56, v57
	v_cvt_pk_bf16_f32 v56, v50, v51
	v_cvt_pk_bf16_f32 v57, v52, v53
	ds_write_b128 v251, v[54:57]
	ds_read_b128 v[54:57], v252
	v_add_u32_e32 v253, 0x80000, v145
	s_waitcnt lgkmcnt(4)
	global_store_dwordx4 v253, v[62:65], s[16:17]
	v_cvt_pk_bf16_f32 v30, v30, v31
	v_cvt_pk_bf16_f32 v31, v32, v33
	v_cvt_pk_bf16_f32 v32, v26, v27
	v_cvt_pk_bf16_f32 v33, v28, v29
	ds_write_b128 v251, v[30:33]
	ds_read_b128 v[30:33], v252
	s_waitcnt lgkmcnt(4)
	global_store_dwordx4 v253, v[46:49], s[16:17] offset:256
	v_cvt_pk_bf16_f32 v38, v38, v39
	v_cvt_pk_bf16_f32 v39, v40, v41
	v_cvt_pk_bf16_f32 v40, v34, v35
	v_cvt_pk_bf16_f32 v41, v36, v37
	ds_write_b128 v251, v[38:41]
	ds_read_b128 v[38:41], v252
	v_add_u32_e32 v253, 0x90000, v145
	s_waitcnt lgkmcnt(4)
	global_store_dwordx4 v253, v[54:57], s[16:17]
	v_cvt_pk_bf16_f32 v14, v14, v15
	v_cvt_pk_bf16_f32 v15, v16, v17
	v_cvt_pk_bf16_f32 v16, v10, v11
	v_cvt_pk_bf16_f32 v17, v12, v13
	ds_write_b128 v251, v[14:17]
	ds_read_b128 v[14:17], v252
	s_waitcnt lgkmcnt(4)
	global_store_dwordx4 v253, v[30:33], s[16:17] offset:256
	v_cvt_pk_bf16_f32 v22, v22, v23
	v_cvt_pk_bf16_f32 v23, v24, v25
	v_cvt_pk_bf16_f32 v24, v18, v19
	v_cvt_pk_bf16_f32 v25, v20, v21
	ds_write_b128 v251, v[22:25]
	ds_read_b128 v[22:25], v252
	v_add_u32_e32 v253, 0xa0000, v145
	s_waitcnt lgkmcnt(4)
	global_store_dwordx4 v253, v[38:41], s[16:17]
	v_cvt_pk_bf16_f32 v6, v6, v7
	v_cvt_pk_bf16_f32 v7, v8, v9
	v_cvt_pk_bf16_f32 v8, v2, v3
	v_cvt_pk_bf16_f32 v9, v4, v5
	ds_write_b128 v251, v[6:9]
	ds_read_b128 v[6:9], v252
	s_waitcnt lgkmcnt(4)
	global_store_dwordx4 v253, v[14:17], s[16:17] offset:256
	v_add_u32_e32 v253, 0xb0000, v145
	s_waitcnt lgkmcnt(2)
	global_store_dwordx4 v253, v[22:25], s[16:17]
	s_waitcnt lgkmcnt(0)
	global_store_dwordx4 v253, v[6:9], s[16:17] offset:256
.Lg3_done:
	s_mov_b64 s[46:47], s[80:81]
	s_mov_b32 s45, s97
	s_mov_b32 s48, 0xffcf4000
	s_movk_i32 s49, 0x3fff
	s_branch .LBB0_17
